# v054 + P9 in-proj epilogue: 8 ss-row loads hoisted (one wait) so the per-group vmcnt(0) no longer serializes the store drain
# speedup vs baseline: 1.0113x; 1.0113x over previous
; #define G_STAGE(bufoff, gbase, voff) do { _Pragma("unroll") for (int _i = 0; _i < 2; ++_i) \
;         __builtin_amdgcn_global_load_lds((const unsigned*)((const char*)(gbase) + (voff)[_i]), (LAS unsigned*)(lds + (bufoff) + ldsw + _i * 8192), 16, 0, 0); } while (0)
; #define G_LDA(dst, b, h) do { _Pragma("unroll") for (int m = 0; m < 4; ++m) _Pragma("unroll") for (int k = 0; k < 2; ++k) dst[m][k] = *(const LAS bf16x8*)(lds + G_SA(b, h) + aoff + m * 2048 + k * 1024); } while (0)
; #define G_LDB(dst, b, h) do { _Pragma("unroll") for (int n = 0; n < 2; ++n) _Pragma("unroll") for (int k = 0; k < 2; ++k) dst[n][k] = *(const LAS bf16x8*)(lds + G_SB(b, h) + boff + n * 2048 + k * 1024); } while (0)
; #define G_MMA(ai, bj, At, Bt) do { __builtin_amdgcn_s_setprio(1); _Pragma("unroll") for (int m = 0; m < 4; ++m) _Pragma("unroll") for (int n = 0; n < 2; ++n) _Pragma("unroll") for (int k = 0; k < 2; ++k) \
;         acc[ai][bj][m][n] = __builtin_amdgcn_mfma_f32_16x16x32_bf16(Bt[n][k], At[m][k], acc[ai][bj][m][n], 0, 0, 0); __builtin_amdgcn_s_setprio(0); } while (0)
; #define G_WAIT_V(n) asm volatile("s_waitcnt vmcnt(" #n ")" ::: "memory")
; #define G_WAIT_L(n) asm volatile("s_waitcnt lgkmcnt(" #n ")" ::: "memory")
; #define G_BAR __builtin_amdgcn_s_barrier()
; #define G_SCHED __builtin_amdgcn_sched_barrier(0)
; template <bool PERM, class Dec, class Epi>
; DI void gemm_phase(LAS unsigned char* lds, const int nM, const int nN, const int K, const int lda, const int ldb, const Dec& dec, const Epi& epi, const int vb, const int panel = -1) {
;     ...
;             G_LDB(B0, 0, 0); G_SCHED; G_LDA(At, 0, 0); G_STAGE(G_SA(1, 1), a1 + hstepA, voffA);
;             G_WAIT_L(8); G_BAR; G_WAIT_L(0); G_MMA(0, 0, At, B0); G_BAR; G_SCHED;
;             G_LDB(B1, 0, 1); G_STAGE(G_SB(0, 0), b2, voffB);
;             G_BAR; G_WAIT_L(0); G_MMA(0, 1, At, B1); G_BAR;
;             G_LDA(At, 0, 1); G_STAGE(G_SA(0, 0), a2, voffA);
;             G_BAR; G_WAIT_L(0); G_MMA(1, 0, At, B0); G_BAR; G_SCHED;
;             G_STAGE(G_SB(0, 1), b2 + hstepB, voffB);
;             G_WAIT_V(6); G_BAR; G_MMA(1, 1, At, B1); G_BAR;
;             G_LDB(B0, 1, 0); G_SCHED; G_LDA(At, 1, 0); G_STAGE(G_SA(0, 1), a2 + hstepA, voffA);
;             G_WAIT_L(8); G_BAR; G_WAIT_L(0); G_MMA(0, 0, At, B0); G_BAR; G_SCHED;
.LBB0_752:
	s_add_u32 s28, s2, 0xfffc0080
	s_addc_u32 s29, s3, -1
	s_add_i32 s68, 0, 0x10000
	v_add_u32_e32 v172, s68, v177
	ds_read_b128 v[128:131], v172
	ds_read_b128 v[168:171], v172 offset:1024
	ds_read_b128 v[180:183], v172 offset:2048
	ds_read_b128 v[184:187], v172 offset:3072
	s_cmp_eq_u32 s76, 12
	s_cselect_b32 s31, s27, s29
	s_cselect_b32 s30, s33, s28
	s_cselect_b32 s29, s38, s53
	s_cselect_b32 s28, s39, s51
	v_lshl_add_u64 v[172:173], s[2:3], 0, v[164:165]
	s_add_i32 m0, s36, 0xc000
	ds_read_b128 v[188:191], v178
	ds_read_b128 v[194:197], v178 offset:1024
	ds_read_b128 v[198:201], v178 offset:2048
	ds_read_b128 v[202:205], v178 offset:3072
	ds_read_b128 v[206:209], v178 offset:4096
	ds_read_b128 v[210:213], v178 offset:5120
	ds_read_b128 v[214:217], v178 offset:6144
	ds_read_b128 v[218:221], v178 offset:7168
	global_load_lds_dwordx4 v[172:173], off
	v_lshl_add_u64 v[172:173], s[2:3], 0, v[166:167]
	s_add_i32 m0, s36, 0xe000
	s_nop 0
	global_load_lds_dwordx4 v[172:173], off
	s_waitcnt lgkmcnt(8)
	s_barrier
	s_waitcnt lgkmcnt(0)
	s_setprio 1
	s_waitcnt lgkmcnt(0)
	v_mfma_f32_16x16x32_bf16 v[124:127], v[128:131], v[188:191], v[124:127]
	v_mfma_f32_16x16x32_bf16 v[120:123], v[180:183], v[188:191], v[120:123]
	v_mfma_f32_16x16x32_bf16 v[112:115], v[128:131], v[198:201], v[112:115]
	v_mfma_f32_16x16x32_bf16 v[104:107], v[180:183], v[198:201], v[104:107]
	v_mfma_f32_16x16x32_bf16 v[96:99], v[128:131], v[206:209], v[96:99]
	v_mfma_f32_16x16x32_bf16 v[88:91], v[180:183], v[206:209], v[88:91]
	v_mfma_f32_16x16x32_bf16 v[80:83], v[128:131], v[214:217], v[80:83]
	v_mfma_f32_16x16x32_bf16 v[72:75], v[180:183], v[214:217], v[72:75]
	v_mfma_f32_16x16x32_bf16 v[124:127], v[168:171], v[194:197], v[124:127]
	v_mfma_f32_16x16x32_bf16 v[120:123], v[184:187], v[194:197], v[120:123]
	v_mfma_f32_16x16x32_bf16 v[112:115], v[168:171], v[202:205], v[112:115]
	v_mfma_f32_16x16x32_bf16 v[104:107], v[184:187], v[202:205], v[104:107]
	v_mfma_f32_16x16x32_bf16 v[96:99], v[168:171], v[210:213], v[96:99]
	v_mfma_f32_16x16x32_bf16 v[88:91], v[184:187], v[210:213], v[88:91]
	v_mfma_f32_16x16x32_bf16 v[80:83], v[168:171], v[218:221], v[80:83]
	v_mfma_f32_16x16x32_bf16 v[72:75], v[184:187], v[218:221], v[72:75]
	s_setprio 0
	s_barrier
	s_add_i32 s77, 0, 0x14000
	v_add_u32_e32 v172, s77, v177
	s_add_i32 s68, s68, s35
	ds_read_b128 v[222:225], v172
	ds_read_b128 v[226:229], v172 offset:1024
	ds_read_b128 v[230:233], v172 offset:2048
	ds_read_b128 v[234:237], v172 offset:3072
	v_lshl_add_u64 v[172:173], s[28:29], 0, v[142:143]
	s_mov_b32 m0, s68
	v_lshl_add_u64 v[238:239], s[28:29], 0, v[138:139]
	global_load_lds_dwordx4 v[172:173], off
	s_add_i32 m0, s68, 0x2000
	s_nop 0
	global_load_lds_dwordx4 v[238:239], off
	s_barrier
	s_waitcnt lgkmcnt(0)
	s_setprio 1
	s_waitcnt lgkmcnt(0)
	v_mfma_f32_16x16x32_bf16 v[116:119], v[222:225], v[188:191], v[116:119]
	v_mfma_f32_16x16x32_bf16 v[108:111], v[230:233], v[188:191], v[108:111]
	v_mfma_f32_16x16x32_bf16 v[100:103], v[222:225], v[198:201], v[100:103]
	v_mfma_f32_16x16x32_bf16 v[92:95], v[230:233], v[198:201], v[92:95]
	v_mfma_f32_16x16x32_bf16 v[84:87], v[222:225], v[206:209], v[84:87]
	v_mfma_f32_16x16x32_bf16 v[76:79], v[230:233], v[206:209], v[76:79]
	v_mfma_f32_16x16x32_bf16 v[68:71], v[222:225], v[214:217], v[68:71]
	v_mfma_f32_16x16x32_bf16 v[64:67], v[230:233], v[214:217], v[64:67]
	v_mfma_f32_16x16x32_bf16 v[116:119], v[226:229], v[194:197], v[116:119]
	v_mfma_f32_16x16x32_bf16 v[108:111], v[234:237], v[194:197], v[108:111]
	v_mfma_f32_16x16x32_bf16 v[100:103], v[226:229], v[202:205], v[100:103]
	v_mfma_f32_16x16x32_bf16 v[92:95], v[234:237], v[202:205], v[92:95]
	v_mfma_f32_16x16x32_bf16 v[84:87], v[226:229], v[210:213], v[84:87]
	v_mfma_f32_16x16x32_bf16 v[76:79], v[234:237], v[210:213], v[76:79]
	v_mfma_f32_16x16x32_bf16 v[68:71], v[226:229], v[218:221], v[68:71]
	v_mfma_f32_16x16x32_bf16 v[64:67], v[234:237], v[218:221], v[64:67]
	s_setprio 0
	s_mov_b32 m0, s36
	v_lshl_add_u64 v[240:241], s[30:31], 0, v[144:145]
	s_barrier
	ds_read_b128 v[188:191], v178 offset:16384
	ds_read_b128 v[194:197], v178 offset:17408
	ds_read_b128 v[198:201], v178 offset:18432
	ds_read_b128 v[202:205], v178 offset:19456
	ds_read_b128 v[206:209], v178 offset:20480
	ds_read_b128 v[210:213], v178 offset:21504
	ds_read_b128 v[214:217], v178 offset:22528
	ds_read_b128 v[218:221], v178 offset:23552
	global_load_lds_dwordx4 v[240:241], off
	v_lshl_add_u64 v[242:243], s[30:31], 0, v[140:141]
	s_mov_b32 m0, s37
	s_nop 0
	global_load_lds_dwordx4 v[242:243], off
	s_barrier
	s_waitcnt lgkmcnt(0)
	s_setprio 1
	s_waitcnt lgkmcnt(0)
	v_mfma_f32_16x16x32_bf16 v[60:63], v[128:131], v[188:191], v[60:63]
	v_mfma_f32_16x16x32_bf16 v[56:59], v[180:183], v[188:191], v[56:59]
	v_mfma_f32_16x16x32_bf16 v[48:51], v[128:131], v[198:201], v[48:51]
	v_mfma_f32_16x16x32_bf16 v[40:43], v[180:183], v[198:201], v[40:43]
	v_mfma_f32_16x16x32_bf16 v[32:35], v[128:131], v[206:209], v[32:35]
	v_mfma_f32_16x16x32_bf16 v[24:27], v[180:183], v[206:209], v[24:27]
	v_mfma_f32_16x16x32_bf16 v[16:19], v[128:131], v[214:217], v[16:19]
	v_mfma_f32_16x16x32_bf16 v[8:11], v[180:183], v[214:217], v[8:11]
	v_mfma_f32_16x16x32_bf16 v[60:63], v[168:171], v[194:197], v[60:63]
	v_mfma_f32_16x16x32_bf16 v[56:59], v[184:187], v[194:197], v[56:59]
	v_mfma_f32_16x16x32_bf16 v[48:51], v[168:171], v[202:205], v[48:51]
	v_mfma_f32_16x16x32_bf16 v[40:43], v[184:187], v[202:205], v[40:43]
	v_mfma_f32_16x16x32_bf16 v[32:35], v[168:171], v[210:213], v[32:35]
	v_mfma_f32_16x16x32_bf16 v[24:27], v[184:187], v[210:213], v[24:27]
	v_mfma_f32_16x16x32_bf16 v[16:19], v[168:171], v[218:221], v[16:19]
	v_mfma_f32_16x16x32_bf16 v[8:11], v[184:187], v[218:221], v[8:11]
	s_setprio 0
	s_barrier
; #define G_STAGE(bufoff, gbase, voff) do { _Pragma("unroll") for (int _i = 0; _i < 2; ++_i) \
;         __builtin_amdgcn_global_load_lds((const unsigned*)((const char*)(gbase) + (voff)[_i]), (LAS unsigned*)(lds + (bufoff) + ldsw + _i * 8192), 16, 0, 0); } while (0)
; #define G_LDA(dst, b, h) do { _Pragma("unroll") for (int m = 0; m < 4; ++m) _Pragma("unroll") for (int k = 0; k < 2; ++k) dst[m][k] = *(const LAS bf16x8*)(lds + G_SA(b, h) + aoff + m * 2048 + k * 1024); } while (0)
; #define G_LDB(dst, b, h) do { _Pragma("unroll") for (int n = 0; n < 2; ++n) _Pragma("unroll") for (int k = 0; k < 2; ++k) dst[n][k] = *(const LAS bf16x8*)(lds + G_SB(b, h) + boff + n * 2048 + k * 1024); } while (0)
; #define G_MMA(ai, bj, At, Bt) do { __builtin_amdgcn_s_setprio(1); _Pragma("unroll") for (int m = 0; m < 4; ++m) _Pragma("unroll") for (int n = 0; n < 2; ++n) _Pragma("unroll") for (int k = 0; k < 2; ++k) \
;         acc[ai][bj][m][n] = __builtin_amdgcn_mfma_f32_16x16x32_bf16(Bt[n][k], At[m][k], acc[ai][bj][m][n], 0, 0, 0); __builtin_amdgcn_s_setprio(0); } while (0)
; #define G_WAIT_V(n) asm volatile("s_waitcnt vmcnt(" #n ")" ::: "memory")
; #define G_WAIT_L(n) asm volatile("s_waitcnt lgkmcnt(" #n ")" ::: "memory")
; #define G_BAR __builtin_amdgcn_s_barrier()
; #define G_SCHED __builtin_amdgcn_sched_barrier(0)
; template <bool PERM, class Dec, class Epi>
; DI void gemm_phase(LAS unsigned char* lds, const int nM, const int nN, const int K, const int lda, const int ldb, const Dec& dec, const Epi& epi, const int vb, const int panel = -1) {
;     ...
;             G_STAGE(G_SB(0, 1), b2 + hstepB, voffB);
;             G_WAIT_V(6); G_BAR; G_MMA(1, 1, At, B1); G_BAR;
;             G_LDB(B0, 1, 0); G_SCHED; G_LDA(At, 1, 0); G_STAGE(G_SA(0, 1), a2 + hstepA, voffA);
;             G_WAIT_L(8); G_BAR; G_WAIT_L(0); G_MMA(0, 0, At, B0); G_BAR; G_SCHED;
;             G_LDB(B1, 1, 1); G_STAGE(G_SB(1, 0), b3, voffB);
;             G_BAR; G_WAIT_L(0); G_MMA(0, 1, At, B1); G_BAR;
;             G_LDA(At, 1, 1); G_STAGE(G_SA(1, 0), a3, voffA);
	s_add_u32 s68, s28, 0x40000
	s_addc_u32 s69, s29, 0
	s_add_i32 s77, s77, s35
	v_lshl_add_u64 v[128:129], s[68:69], 0, v[142:143]
	s_mov_b32 m0, s77
	s_nop 0
	global_load_lds_dwordx4 v[128:129], off
	v_lshl_add_u64 v[128:129], s[68:69], 0, v[138:139]
	s_add_i32 m0, s77, 0x2000
	s_nop 0
	global_load_lds_dwordx4 v[128:129], off
	s_waitcnt vmcnt(6)
	s_barrier
	s_setprio 1
	v_mfma_f32_16x16x32_bf16 v[52:55], v[222:225], v[188:191], v[52:55]
	v_mfma_f32_16x16x32_bf16 v[44:47], v[230:233], v[188:191], v[44:47]
	v_mfma_f32_16x16x32_bf16 v[36:39], v[222:225], v[198:201], v[36:39]
	v_mfma_f32_16x16x32_bf16 v[28:31], v[230:233], v[198:201], v[28:31]
	v_mfma_f32_16x16x32_bf16 v[20:23], v[222:225], v[206:209], v[20:23]
	v_mfma_f32_16x16x32_bf16 v[12:15], v[230:233], v[206:209], v[12:15]
	v_mfma_f32_16x16x32_bf16 v[4:7], v[222:225], v[214:217], v[4:7]
	v_mfma_f32_16x16x32_bf16 v[0:3], v[230:233], v[214:217], v[0:3]
	v_mfma_f32_16x16x32_bf16 v[52:55], v[226:229], v[194:197], v[52:55]
	v_mfma_f32_16x16x32_bf16 v[44:47], v[234:237], v[194:197], v[44:47]
	v_mfma_f32_16x16x32_bf16 v[36:39], v[226:229], v[202:205], v[36:39]
	v_mfma_f32_16x16x32_bf16 v[28:31], v[234:237], v[202:205], v[28:31]
	v_mfma_f32_16x16x32_bf16 v[20:23], v[226:229], v[210:213], v[20:23]
	v_mfma_f32_16x16x32_bf16 v[12:15], v[234:237], v[210:213], v[12:15]
	v_mfma_f32_16x16x32_bf16 v[4:7], v[226:229], v[218:221], v[4:7]
	v_mfma_f32_16x16x32_bf16 v[0:3], v[234:237], v[218:221], v[0:3]
	s_setprio 0
	s_add_i32 s68, 0, 0x18000
	v_add_u32_e32 v179, s68, v177
	s_barrier
	ds_read_b128 v[128:131], v179
	ds_read_b128 v[168:171], v179 offset:1024
	ds_read_b128 v[180:183], v179 offset:2048
	ds_read_b128 v[184:187], v179 offset:3072
	s_add_u32 s30, s30, 0x40000
	s_addc_u32 s31, s31, 0
	s_mov_b32 m0, s70
	v_lshl_add_u64 v[222:223], s[30:31], 0, v[144:145]
	ds_read_b128 v[188:191], v178 offset:32768
	ds_read_b128 v[194:197], v178 offset:33792
	ds_read_b128 v[198:201], v178 offset:34816
	ds_read_b128 v[202:205], v178 offset:35840
	ds_read_b128 v[206:209], v178 offset:36864
	ds_read_b128 v[210:213], v178 offset:37888
	ds_read_b128 v[214:217], v178 offset:38912
	ds_read_b128 v[218:221], v178 offset:39936
	global_load_lds_dwordx4 v[222:223], off
	v_lshl_add_u64 v[222:223], s[30:31], 0, v[140:141]
	s_mov_b32 m0, s71
	s_nop 0
	global_load_lds_dwordx4 v[222:223], off
	s_waitcnt lgkmcnt(8)
	s_barrier
	s_waitcnt lgkmcnt(0)
	s_setprio 1
	s_waitcnt lgkmcnt(0)
	v_mfma_f32_16x16x32_bf16 v[124:127], v[128:131], v[188:191], v[124:127]
	v_mfma_f32_16x16x32_bf16 v[120:123], v[180:183], v[188:191], v[120:123]
	v_mfma_f32_16x16x32_bf16 v[112:115], v[128:131], v[198:201], v[112:115]
	v_mfma_f32_16x16x32_bf16 v[104:107], v[180:183], v[198:201], v[104:107]
	v_mfma_f32_16x16x32_bf16 v[96:99], v[128:131], v[206:209], v[96:99]
	v_mfma_f32_16x16x32_bf16 v[88:91], v[180:183], v[206:209], v[88:91]
	v_mfma_f32_16x16x32_bf16 v[80:83], v[128:131], v[214:217], v[80:83]
	v_mfma_f32_16x16x32_bf16 v[72:75], v[180:183], v[214:217], v[72:75]
	v_mfma_f32_16x16x32_bf16 v[124:127], v[168:171], v[194:197], v[124:127]
	v_mfma_f32_16x16x32_bf16 v[120:123], v[184:187], v[194:197], v[120:123]
	v_mfma_f32_16x16x32_bf16 v[112:115], v[168:171], v[202:205], v[112:115]
	v_mfma_f32_16x16x32_bf16 v[104:107], v[184:187], v[202:205], v[104:107]
	v_mfma_f32_16x16x32_bf16 v[96:99], v[168:171], v[210:213], v[96:99]
	v_mfma_f32_16x16x32_bf16 v[88:91], v[184:187], v[210:213], v[88:91]
	v_mfma_f32_16x16x32_bf16 v[80:83], v[168:171], v[218:221], v[80:83]
	v_mfma_f32_16x16x32_bf16 v[72:75], v[184:187], v[218:221], v[72:75]
	s_setprio 0
	s_barrier
	s_add_i32 s30, 0, 0x1c000
	s_add_i32 s31, s68, s35
	v_add_u32_e32 v179, s30, v177
	v_lshl_add_u64 v[172:173], v[172:173], 0, s[48:49]
	s_mov_b32 m0, s31
	ds_read_b128 v[222:225], v179
	ds_read_b128 v[226:229], v179 offset:1024
	ds_read_b128 v[230:233], v179 offset:2048
	ds_read_b128 v[234:237], v179 offset:3072
	global_load_lds_dwordx4 v[172:173], off
	v_lshl_add_u64 v[172:173], v[238:239], 0, s[48:49]
	s_add_i32 m0, s31, 0x2000
	s_nop 0
	global_load_lds_dwordx4 v[172:173], off
	s_barrier
	s_waitcnt lgkmcnt(0)
	s_setprio 1
	s_waitcnt lgkmcnt(0)
	v_mfma_f32_16x16x32_bf16 v[116:119], v[222:225], v[188:191], v[116:119]
	v_mfma_f32_16x16x32_bf16 v[108:111], v[230:233], v[188:191], v[108:111]
	v_mfma_f32_16x16x32_bf16 v[100:103], v[222:225], v[198:201], v[100:103]
	v_mfma_f32_16x16x32_bf16 v[92:95], v[230:233], v[198:201], v[92:95]
	v_mfma_f32_16x16x32_bf16 v[84:87], v[222:225], v[206:209], v[84:87]
	v_mfma_f32_16x16x32_bf16 v[76:79], v[230:233], v[206:209], v[76:79]
	v_mfma_f32_16x16x32_bf16 v[68:71], v[222:225], v[214:217], v[68:71]
	v_mfma_f32_16x16x32_bf16 v[64:67], v[230:233], v[214:217], v[64:67]
	v_mfma_f32_16x16x32_bf16 v[116:119], v[226:229], v[194:197], v[116:119]
	v_mfma_f32_16x16x32_bf16 v[108:111], v[234:237], v[194:197], v[108:111]
	v_mfma_f32_16x16x32_bf16 v[100:103], v[226:229], v[202:205], v[100:103]
	v_mfma_f32_16x16x32_bf16 v[92:95], v[234:237], v[202:205], v[92:95]
	v_mfma_f32_16x16x32_bf16 v[84:87], v[226:229], v[210:213], v[84:87]
	v_mfma_f32_16x16x32_bf16 v[76:79], v[234:237], v[210:213], v[76:79]
	v_mfma_f32_16x16x32_bf16 v[68:71], v[226:229], v[218:221], v[68:71]
	v_mfma_f32_16x16x32_bf16 v[64:67], v[234:237], v[218:221], v[64:67]
	s_setprio 0
	s_mov_b32 m0, s72
	v_lshl_add_u64 v[172:173], v[240:241], 0, s[48:49]
	s_barrier
	ds_read_b128 v[188:191], v178 offset:49152
	ds_read_b128 v[194:197], v178 offset:50176
	ds_read_b128 v[198:201], v178 offset:51200
	ds_read_b128 v[202:205], v178 offset:52224
	ds_read_b128 v[206:209], v178 offset:53248
	ds_read_b128 v[210:213], v178 offset:54272
	ds_read_b128 v[214:217], v178 offset:55296
	ds_read_b128 v[218:221], v178 offset:56320
	global_load_lds_dwordx4 v[172:173], off
	v_lshl_add_u64 v[172:173], v[242:243], 0, s[48:49]
	s_mov_b32 m0, s73
	s_nop 0
	global_load_lds_dwordx4 v[172:173], off
	s_barrier
; DI unsigned pk2(float a, float b) { f32x2 v = {a, b}; bf2_t r = __builtin_convertvector(v, bf2_t); return __builtin_bit_cast(unsigned, r); }
; DI float sigm(float x) { return __builtin_amdgcn_rcpf(1.f + __expf(-x)); }
; DI float silu_(float x) { return x * __builtin_amdgcn_rcpf(1.f + __expf(-x)); }
; #define G_STAGE(bufoff, gbase, voff) do { _Pragma("unroll") for (int _i = 0; _i < 2; ++_i) \
;         __builtin_amdgcn_global_load_lds((const unsigned*)((const char*)(gbase) + (voff)[_i]), (LAS unsigned*)(lds + (bufoff) + ldsw + _i * 8192), 16, 0, 0); } while (0)
; #define G_WAIT_V(n) asm volatile("s_waitcnt vmcnt(" #n ")" ::: "memory")
; #define G_WAIT_L(n) asm volatile("s_waitcnt lgkmcnt(" #n ")" ::: "memory")
; #define G_BAR __builtin_amdgcn_s_barrier()
; #define G_SCHED __builtin_amdgcn_sched_barrier(0)
; template <bool PERM, class Dec, class Epi>
; DI void gemm_phase(LAS unsigned char* lds, const int nM, const int nN, const int K, const int lda, const int ldb, const Dec& dec, const Epi& epi, const int vb, const int panel = -1) {
;     ...
;             G_BAR; G_WAIT_L(0); G_MMA(1, 0, At, B0); G_BAR; G_SCHED;
;             G_STAGE(G_SB(1, 1), b3 + hstepB, voffB);
;             G_WAIT_V(6); G_BAR; G_MMA(1, 1, At, B1); G_BAR;
; template <int ACT>
; DI void epi_bf16(const f32x4 (&acc)[2][2][4][2], bf16_t* O, const int ldc, int wr, int wc, int fr, int fq, const float* ssrow = nullptr) {
; #pragma unroll
;     for (int ai = 0; ai < 2; ++ai)
; #pragma unroll
;         for (int m = 0; m < 4; ++m) {
;             bf16_t* rowp = O + (size_t)(ai * HALF + wr * 64 + m * 16 + fr) * ldc + wc * 32 + 8 * fq;
;             const float rsc = ssrow ? __builtin_amdgcn_rsqf(ssrow[ai * HALF + wr * 64 + m * 16 + fr] * (1.f / 1024.f) + EPS_) : 1.f;
; #pragma unroll
;             for (int bj = 0; bj < 2; ++bj) {
;                 f32x4 v0 = acc[ai][bj][m][0] * rsc, v1 = acc[ai][bj][m][1] * rsc;
;                 if (ACT == 1) {
; #pragma unroll
;                     for (int j = 0; j < 4; ++j) { v0[j] = silu_(v0[j]); v1[j] = silu_(v1[j]); } }
;                 if (ACT == 2) {
; #pragma unroll
;                     for (int j = 0; j < 4; ++j) { v0[j] = sigm(v0[j]); v1[j] = sigm(v1[j]); } }
;                 u32x4 w; w[0] = pk2(v0[0], v0[1]); w[1] = pk2(v0[2], v0[3]); w[2] = pk2(v1[0], v1[1]); w[3] = pk2(v1[2], v1[3]);
;                 *(u32x4*)(rowp + bj * HALF) = w;
	s_waitcnt lgkmcnt(0)
	s_setprio 1
	s_waitcnt lgkmcnt(0)
	v_mfma_f32_16x16x32_bf16 v[60:63], v[128:131], v[188:191], v[60:63]
	v_mfma_f32_16x16x32_bf16 v[56:59], v[180:183], v[188:191], v[56:59]
	v_mfma_f32_16x16x32_bf16 v[48:51], v[128:131], v[198:201], v[48:51]
	v_mfma_f32_16x16x32_bf16 v[40:43], v[180:183], v[198:201], v[40:43]
	v_mfma_f32_16x16x32_bf16 v[32:35], v[128:131], v[206:209], v[32:35]
	v_mfma_f32_16x16x32_bf16 v[24:27], v[180:183], v[206:209], v[24:27]
	v_mfma_f32_16x16x32_bf16 v[16:19], v[128:131], v[214:217], v[16:19]
	v_mfma_f32_16x16x32_bf16 v[8:11], v[180:183], v[214:217], v[8:11]
	v_mfma_f32_16x16x32_bf16 v[60:63], v[168:171], v[194:197], v[60:63]
	v_mfma_f32_16x16x32_bf16 v[56:59], v[184:187], v[194:197], v[56:59]
	v_mfma_f32_16x16x32_bf16 v[48:51], v[168:171], v[202:205], v[48:51]
	v_mfma_f32_16x16x32_bf16 v[40:43], v[184:187], v[202:205], v[40:43]
	v_mfma_f32_16x16x32_bf16 v[32:35], v[168:171], v[210:213], v[32:35]
	v_mfma_f32_16x16x32_bf16 v[24:27], v[184:187], v[210:213], v[24:27]
	v_mfma_f32_16x16x32_bf16 v[16:19], v[168:171], v[218:221], v[16:19]
	v_mfma_f32_16x16x32_bf16 v[8:11], v[184:187], v[218:221], v[8:11]
	s_setprio 0
	s_barrier
	s_add_u32 s28, s28, 0x40080
	s_addc_u32 s29, s29, 0
	s_add_i32 s30, s30, s35
	v_lshl_add_u64 v[128:129], s[28:29], 0, v[142:143]
	s_mov_b32 m0, s30
	s_nop 0
	global_load_lds_dwordx4 v[128:129], off
	v_lshl_add_u64 v[128:129], s[28:29], 0, v[138:139]
	s_add_i32 m0, s30, 0x2000
	s_nop 0
	global_load_lds_dwordx4 v[128:129], off
	s_waitcnt vmcnt(6)
	s_barrier
	s_setprio 1
	v_mfma_f32_16x16x32_bf16 v[52:55], v[222:225], v[188:191], v[52:55]
	v_mfma_f32_16x16x32_bf16 v[44:47], v[230:233], v[188:191], v[44:47]
	v_mfma_f32_16x16x32_bf16 v[36:39], v[222:225], v[198:201], v[36:39]
	v_mfma_f32_16x16x32_bf16 v[28:31], v[230:233], v[198:201], v[28:31]
	v_mfma_f32_16x16x32_bf16 v[20:23], v[222:225], v[206:209], v[20:23]
	v_mfma_f32_16x16x32_bf16 v[12:15], v[230:233], v[206:209], v[12:15]
	v_mfma_f32_16x16x32_bf16 v[4:7], v[222:225], v[214:217], v[4:7]
	v_mfma_f32_16x16x32_bf16 v[0:3], v[230:233], v[214:217], v[0:3]
	v_mfma_f32_16x16x32_bf16 v[52:55], v[226:229], v[194:197], v[52:55]
	v_mfma_f32_16x16x32_bf16 v[44:47], v[234:237], v[194:197], v[44:47]
	v_mfma_f32_16x16x32_bf16 v[36:39], v[226:229], v[202:205], v[36:39]
	v_mfma_f32_16x16x32_bf16 v[28:31], v[234:237], v[202:205], v[28:31]
	v_mfma_f32_16x16x32_bf16 v[20:23], v[226:229], v[210:213], v[20:23]
	v_mfma_f32_16x16x32_bf16 v[12:15], v[234:237], v[210:213], v[12:15]
	v_mfma_f32_16x16x32_bf16 v[4:7], v[226:229], v[218:221], v[4:7]
	v_mfma_f32_16x16x32_bf16 v[0:3], v[234:237], v[218:221], v[0:3]
	s_setprio 0
	s_add_i32 s76, s76, 2
	s_add_u32 s2, s2, 0x100
	s_addc_u32 s3, s3, 0
	s_add_u32 s51, s51, 0x100
	s_addc_u32 s53, s53, 0
	s_cmp_gt_u32 s76, 13
	s_barrier
	s_cbranch_scc0 .LBB0_752
	s_lshl_b32 s2, s4, 8
	s_ashr_i32 s3, s2, 31
	s_lshl_b64 s[2:3], s[2:3], 2
	s_add_u32 s28, s86, s2
	s_addc_u32 s29, s87, s3
	s_lshl_b32 s30, s15, 8
	s_cmp_gt_i32 s15, 5
	s_mul_hi_i32 s15, s4, 0xc0000
	s_mul_i32 s27, s4, 0xc0000
	s_mov_b64 s[2:3], -1
	v_lshl_add_u64 v[168:169], v[146:147], 2, s[28:29]
	s_cbranch_scc0 .LBB0_755
	global_load_dword v236, v[168:169], off
	global_load_dword v237, v[168:169], off offset:64
	global_load_dword v238, v[168:169], off offset:128
	global_load_dword v239, v[168:169], off offset:192
	global_load_dword v240, v[168:169], off offset:512
	global_load_dword v241, v[168:169], off offset:576
	global_load_dword v242, v[168:169], off offset:640
	global_load_dword v243, v[168:169], off offset:704
	s_add_u32 s28, s16, s27
	s_addc_u32 s29, s17, s15
	s_add_i32 s4, s30, 0xfffffa00
	s_lshl_b64 s[2:3], s[4:5], 1
	s_add_u32 s28, s28, s2
	s_addc_u32 s29, s29, s3
	s_lshl_b32 s2, s74, 1
	s_add_u32 s2, s28, s2
	s_addc_u32 s3, s29, 0
	v_lshl_add_u64 v[128:129], s[2:3], 0, v[132:133]
	v_lshl_add_u64 v[130:131], v[128:129], 0, v[148:149]
	s_mov_b64 s[2:3], 0
	s_waitcnt vmcnt(0)
	v_mov_b32_e32 v170, v236
	v_fmamk_f32 v170, v170, 0x3a800000, v175
	v_rsq_f32_e32 v180, v170
	s_nop 0
	v_pk_mul_f32 v[172:173], v[124:125], v[180:181] op_sel_hi:[1,0]
	s_nop 0
	v_mul_f32_e32 v179, 0xbfb8aa3b, v172
	v_exp_f32_e32 v179, v179
	v_pk_mul_f32 v[184:185], v[120:121], v[180:181] op_sel_hi:[1,0]
	v_pk_mul_f32 v[170:171], v[126:127], v[180:181] op_sel_hi:[1,0]
	v_pk_mul_f32 v[182:183], v[122:123], v[180:181] op_sel_hi:[1,0]
	v_add_f32_e32 v179, 1.0, v179
	v_rcp_f32_e32 v186, v179
	v_mul_f32_e32 v179, 0xbfb8aa3b, v184
	v_exp_f32_e32 v179, v179
	s_nop 0
	v_add_f32_e32 v179, 1.0, v179
	v_rcp_f32_e32 v188, v179
	v_mul_f32_e32 v179, 0xbfb8aa3b, v173
	v_exp_f32_e32 v179, v179
	s_nop 0
	v_add_f32_e32 v179, 1.0, v179
	v_rcp_f32_e32 v187, v179
	v_mul_f32_e32 v179, 0xbfb8aa3b, v185
	v_exp_f32_e32 v179, v179
	v_pk_mul_f32 v[172:173], v[172:173], v[186:187]
	v_add_f32_e32 v179, 1.0, v179
	v_rcp_f32_e32 v189, v179
	v_mul_f32_e32 v179, 0xbfb8aa3b, v170
	v_exp_f32_e32 v179, v179
	v_pk_mul_f32 v[184:185], v[184:185], v[188:189]
	v_add_f32_e32 v179, 1.0, v179
	v_rcp_f32_e32 v186, v179
	v_mul_f32_e32 v179, 0xbfb8aa3b, v182
	v_exp_f32_e32 v179, v179
	s_nop 0
	v_add_f32_e32 v179, 1.0, v179
	v_rcp_f32_e32 v188, v179
	v_mul_f32_e32 v179, 0xbfb8aa3b, v171
	v_exp_f32_e32 v179, v179
	s_nop 0
	v_add_f32_e32 v179, 1.0, v179
	v_rcp_f32_e32 v187, v179
	s_nop 0
	v_pk_mul_f32 v[186:187], v[170:171], v[186:187]
	v_mul_f32_e32 v170, 0xbfb8aa3b, v183
	v_exp_f32_e32 v170, v170
	v_cvt_pk_bf16_f32 v171, v186, v187
	v_add_f32_e32 v170, 1.0, v170
	v_rcp_f32_e32 v189, v170
	v_cvt_pk_bf16_f32 v170, v172, v173
	v_cvt_pk_bf16_f32 v172, v184, v185
	v_pk_mul_f32 v[182:183], v[182:183], v[188:189]
	s_nop 0
; DI unsigned pk2(float a, float b) { f32x2 v = {a, b}; bf2_t r = __builtin_convertvector(v, bf2_t); return __builtin_bit_cast(unsigned, r); }
; DI float sigm(float x) { return __builtin_amdgcn_rcpf(1.f + __expf(-x)); }
; DI float silu_(float x) { return x * __builtin_amdgcn_rcpf(1.f + __expf(-x)); }
; template <int ACT>
; DI void epi_bf16(const f32x4 (&acc)[2][2][4][2], bf16_t* O, const int ldc, int wr, int wc, int fr, int fq, const float* ssrow = nullptr) {
;     ...
;             const float rsc = ssrow ? __builtin_amdgcn_rsqf(ssrow[ai * HALF + wr * 64 + m * 16 + fr] * (1.f / 1024.f) + EPS_) : 1.f;
; #pragma unroll
;             for (int bj = 0; bj < 2; ++bj) {
;                 f32x4 v0 = acc[ai][bj][m][0] * rsc, v1 = acc[ai][bj][m][1] * rsc;
;                 if (ACT == 1) {
; #pragma unroll
;                     for (int j = 0; j < 4; ++j) { v0[j] = silu_(v0[j]); v1[j] = silu_(v1[j]); } }
;                 if (ACT == 2) {
; #pragma unroll
;                     for (int j = 0; j < 4; ++j) { v0[j] = sigm(v0[j]); v1[j] = sigm(v1[j]); } }
;                 u32x4 w; w[0] = pk2(v0[0], v0[1]); w[1] = pk2(v0[2], v0[3]); w[2] = pk2(v1[0], v1[1]); w[3] = pk2(v1[2], v1[3]);
;                 *(u32x4*)(rowp + bj * HALF) = w;
	v_cvt_pk_bf16_f32 v173, v182, v183
	global_store_dwordx4 v[130:131], v[170:173], off
	v_pk_mul_f32 v[182:183], v[118:119], v[180:181] op_sel_hi:[1,0]
	s_nop 0
	v_pk_mul_f32 v[172:173], v[116:117], v[180:181] op_sel_hi:[1,0]
	v_pk_mul_f32 v[170:171], v[110:111], v[180:181] op_sel_hi:[1,0]
	v_mul_f32_e32 v179, 0xbfb8aa3b, v172
	v_exp_f32_e32 v179, v179
	v_pk_mul_f32 v[180:181], v[108:109], v[180:181] op_sel_hi:[1,0]
	v_add_f32_e32 v179, 1.0, v179
	v_rcp_f32_e32 v184, v179
	v_mul_f32_e32 v179, 0xbfb8aa3b, v180
	v_exp_f32_e32 v179, v179
	s_nop 0
	v_add_f32_e32 v179, 1.0, v179
	v_rcp_f32_e32 v186, v179
	v_mul_f32_e32 v179, 0xbfb8aa3b, v173
	v_exp_f32_e32 v179, v179
	s_nop 0
	v_add_f32_e32 v179, 1.0, v179
	v_rcp_f32_e32 v185, v179
	v_mul_f32_e32 v179, 0xbfb8aa3b, v181
	v_exp_f32_e32 v179, v179
	v_pk_mul_f32 v[172:173], v[172:173], v[184:185]
	v_add_f32_e32 v179, 1.0, v179
	v_rcp_f32_e32 v187, v179
	v_mul_f32_e32 v179, 0xbfb8aa3b, v182
	v_exp_f32_e32 v179, v179
	v_pk_mul_f32 v[180:181], v[180:181], v[186:187]
	v_add_f32_e32 v179, 1.0, v179
	v_rcp_f32_e32 v184, v179
	v_mul_f32_e32 v179, 0xbfb8aa3b, v170
	v_exp_f32_e32 v179, v179
	s_nop 0
	v_add_f32_e32 v179, 1.0, v179
	v_rcp_f32_e32 v186, v179
	v_mul_f32_e32 v179, 0xbfb8aa3b, v183
	v_exp_f32_e32 v179, v179
	s_nop 0
	v_add_f32_e32 v179, 1.0, v179
	v_rcp_f32_e32 v185, v179
	v_mul_f32_e32 v179, 0xbfb8aa3b, v171
	v_exp_f32_e32 v179, v179
	v_pk_mul_f32 v[182:183], v[182:183], v[184:185]
	v_add_f32_e32 v179, 1.0, v179
	v_rcp_f32_e32 v187, v179
	s_nop 0
	v_pk_mul_f32 v[184:185], v[170:171], v[186:187]
	v_cvt_pk_bf16_f32 v170, v172, v173
	v_cvt_pk_bf16_f32 v171, v182, v183
	v_cvt_pk_bf16_f32 v172, v180, v181
	v_cvt_pk_bf16_f32 v173, v184, v185
	global_store_dwordx4 v[130:131], v[170:173], off offset:256
	v_lshl_add_u64 v[130:131], v[128:129], 0, v[150:151]
	s_nop 1
	v_mov_b32_e32 v170, v237
	v_fmamk_f32 v170, v170, 0x3a800000, v175
	v_rsq_f32_e32 v180, v170
	s_nop 0
	v_pk_mul_f32 v[172:173], v[112:113], v[180:181] op_sel_hi:[1,0]
	s_nop 0
	v_mul_f32_e32 v179, 0xbfb8aa3b, v172
	v_exp_f32_e32 v179, v179
	v_pk_mul_f32 v[184:185], v[104:105], v[180:181] op_sel_hi:[1,0]
	v_pk_mul_f32 v[170:171], v[114:115], v[180:181] op_sel_hi:[1,0]
	v_pk_mul_f32 v[182:183], v[106:107], v[180:181] op_sel_hi:[1,0]
	v_add_f32_e32 v179, 1.0, v179
	v_rcp_f32_e32 v186, v179
	v_mul_f32_e32 v179, 0xbfb8aa3b, v184
	v_exp_f32_e32 v179, v179
	s_nop 0
	v_add_f32_e32 v179, 1.0, v179
	v_rcp_f32_e32 v188, v179
	v_mul_f32_e32 v179, 0xbfb8aa3b, v173
	v_exp_f32_e32 v179, v179
	s_nop 0
	v_add_f32_e32 v179, 1.0, v179
	v_rcp_f32_e32 v187, v179
	v_mul_f32_e32 v179, 0xbfb8aa3b, v185
	v_exp_f32_e32 v179, v179
	v_pk_mul_f32 v[172:173], v[172:173], v[186:187]
	v_add_f32_e32 v179, 1.0, v179
	v_rcp_f32_e32 v189, v179
	v_mul_f32_e32 v179, 0xbfb8aa3b, v170
	v_exp_f32_e32 v179, v179
	v_pk_mul_f32 v[184:185], v[184:185], v[188:189]
	v_add_f32_e32 v179, 1.0, v179
	v_rcp_f32_e32 v186, v179
	v_mul_f32_e32 v179, 0xbfb8aa3b, v182
	v_exp_f32_e32 v179, v179
	s_nop 0
	v_add_f32_e32 v179, 1.0, v179
	v_rcp_f32_e32 v188, v179
	v_mul_f32_e32 v179, 0xbfb8aa3b, v171
	v_exp_f32_e32 v179, v179
	s_nop 0
	v_add_f32_e32 v179, 1.0, v179
	v_rcp_f32_e32 v187, v179
	s_nop 0
	v_pk_mul_f32 v[186:187], v[170:171], v[186:187]
	v_mul_f32_e32 v170, 0xbfb8aa3b, v183
	v_exp_f32_e32 v170, v170
	v_cvt_pk_bf16_f32 v171, v186, v187
	v_add_f32_e32 v170, 1.0, v170
	v_rcp_f32_e32 v189, v170
	v_cvt_pk_bf16_f32 v170, v172, v173
	v_cvt_pk_bf16_f32 v172, v184, v185
	v_pk_mul_f32 v[182:183], v[182:183], v[188:189]
	s_nop 0
	v_cvt_pk_bf16_f32 v173, v182, v183
	global_store_dwordx4 v[130:131], v[170:173], off
	v_pk_mul_f32 v[182:183], v[102:103], v[180:181] op_sel_hi:[1,0]
	s_nop 0
	v_pk_mul_f32 v[172:173], v[100:101], v[180:181] op_sel_hi:[1,0]
	v_pk_mul_f32 v[170:171], v[94:95], v[180:181] op_sel_hi:[1,0]
	v_mul_f32_e32 v179, 0xbfb8aa3b, v172
	v_exp_f32_e32 v179, v179
	v_pk_mul_f32 v[180:181], v[92:93], v[180:181] op_sel_hi:[1,0]
	v_add_f32_e32 v179, 1.0, v179
	v_rcp_f32_e32 v184, v179
	v_mul_f32_e32 v179, 0xbfb8aa3b, v180
	v_exp_f32_e32 v179, v179
	s_nop 0
	v_add_f32_e32 v179, 1.0, v179
	v_rcp_f32_e32 v186, v179
	v_mul_f32_e32 v179, 0xbfb8aa3b, v173
	v_exp_f32_e32 v179, v179
	s_nop 0
	v_add_f32_e32 v179, 1.0, v179
	v_rcp_f32_e32 v185, v179
	v_mul_f32_e32 v179, 0xbfb8aa3b, v181
	v_exp_f32_e32 v179, v179
	v_pk_mul_f32 v[172:173], v[172:173], v[184:185]
	v_add_f32_e32 v179, 1.0, v179
	v_rcp_f32_e32 v187, v179
	v_mul_f32_e32 v179, 0xbfb8aa3b, v182
	v_exp_f32_e32 v179, v179
	v_pk_mul_f32 v[180:181], v[180:181], v[186:187]
	v_add_f32_e32 v179, 1.0, v179
	v_rcp_f32_e32 v184, v179
	v_mul_f32_e32 v179, 0xbfb8aa3b, v170
	v_exp_f32_e32 v179, v179
	s_nop 0
	v_add_f32_e32 v179, 1.0, v179
	v_rcp_f32_e32 v186, v179
	v_mul_f32_e32 v179, 0xbfb8aa3b, v183
	v_exp_f32_e32 v179, v179
	s_nop 0
	v_add_f32_e32 v179, 1.0, v179
	v_rcp_f32_e32 v185, v179
	v_mul_f32_e32 v179, 0xbfb8aa3b, v171
	v_exp_f32_e32 v179, v179
	v_pk_mul_f32 v[182:183], v[182:183], v[184:185]
	v_add_f32_e32 v179, 1.0, v179
	v_rcp_f32_e32 v187, v179
	s_nop 0
	v_pk_mul_f32 v[184:185], v[170:171], v[186:187]
	v_cvt_pk_bf16_f32 v170, v172, v173
	v_cvt_pk_bf16_f32 v171, v182, v183
	v_cvt_pk_bf16_f32 v172, v180, v181
	v_cvt_pk_bf16_f32 v173, v184, v185
	global_store_dwordx4 v[130:131], v[170:173], off offset:256
	v_lshl_add_u64 v[130:131], v[128:129], 0, v[152:153]
	s_nop 1
	v_mov_b32_e32 v170, v238
	v_fmamk_f32 v170, v170, 0x3a800000, v175
	v_rsq_f32_e32 v180, v170
	s_nop 0
	v_pk_mul_f32 v[172:173], v[96:97], v[180:181] op_sel_hi:[1,0]
	s_nop 0
	v_mul_f32_e32 v179, 0xbfb8aa3b, v172
	v_exp_f32_e32 v179, v179
	v_pk_mul_f32 v[184:185], v[88:89], v[180:181] op_sel_hi:[1,0]
; DI unsigned pk2(float a, float b) { f32x2 v = {a, b}; bf2_t r = __builtin_convertvector(v, bf2_t); return __builtin_bit_cast(unsigned, r); }
; DI float sigm(float x) { return __builtin_amdgcn_rcpf(1.f + __expf(-x)); }
; DI float silu_(float x) { return x * __builtin_amdgcn_rcpf(1.f + __expf(-x)); }
; template <int ACT>
; DI void epi_bf16(const f32x4 (&acc)[2][2][4][2], bf16_t* O, const int ldc, int wr, int wc, int fr, int fq, const float* ssrow = nullptr) {
;     ...
;             const float rsc = ssrow ? __builtin_amdgcn_rsqf(ssrow[ai * HALF + wr * 64 + m * 16 + fr] * (1.f / 1024.f) + EPS_) : 1.f;
; #pragma unroll
;             for (int bj = 0; bj < 2; ++bj) {
;                 f32x4 v0 = acc[ai][bj][m][0] * rsc, v1 = acc[ai][bj][m][1] * rsc;
;                 if (ACT == 1) {
; #pragma unroll
;                     for (int j = 0; j < 4; ++j) { v0[j] = silu_(v0[j]); v1[j] = silu_(v1[j]); } }
;                 if (ACT == 2) {
; #pragma unroll
;                     for (int j = 0; j < 4; ++j) { v0[j] = sigm(v0[j]); v1[j] = sigm(v1[j]); } }
;                 u32x4 w; w[0] = pk2(v0[0], v0[1]); w[1] = pk2(v0[2], v0[3]); w[2] = pk2(v1[0], v1[1]); w[3] = pk2(v1[2], v1[3]);
;                 *(u32x4*)(rowp + bj * HALF) = w;
	v_pk_mul_f32 v[170:171], v[98:99], v[180:181] op_sel_hi:[1,0]
	v_pk_mul_f32 v[182:183], v[90:91], v[180:181] op_sel_hi:[1,0]
	v_add_f32_e32 v179, 1.0, v179
	v_rcp_f32_e32 v186, v179
	v_mul_f32_e32 v179, 0xbfb8aa3b, v184
	v_exp_f32_e32 v179, v179
	s_nop 0
	v_add_f32_e32 v179, 1.0, v179
	v_rcp_f32_e32 v188, v179
	v_mul_f32_e32 v179, 0xbfb8aa3b, v173
	v_exp_f32_e32 v179, v179
	s_nop 0
	v_add_f32_e32 v179, 1.0, v179
	v_rcp_f32_e32 v187, v179
	v_mul_f32_e32 v179, 0xbfb8aa3b, v185
	v_exp_f32_e32 v179, v179
	v_pk_mul_f32 v[172:173], v[172:173], v[186:187]
	v_add_f32_e32 v179, 1.0, v179
	v_rcp_f32_e32 v189, v179
	v_mul_f32_e32 v179, 0xbfb8aa3b, v170
	v_exp_f32_e32 v179, v179
	v_pk_mul_f32 v[184:185], v[184:185], v[188:189]
	v_add_f32_e32 v179, 1.0, v179
	v_rcp_f32_e32 v186, v179
	v_mul_f32_e32 v179, 0xbfb8aa3b, v182
	v_exp_f32_e32 v179, v179
	s_nop 0
	v_add_f32_e32 v179, 1.0, v179
	v_rcp_f32_e32 v188, v179
	v_mul_f32_e32 v179, 0xbfb8aa3b, v171
	v_exp_f32_e32 v179, v179
	s_nop 0
	v_add_f32_e32 v179, 1.0, v179
	v_rcp_f32_e32 v187, v179
	s_nop 0
	v_pk_mul_f32 v[186:187], v[170:171], v[186:187]
	v_mul_f32_e32 v170, 0xbfb8aa3b, v183
	v_exp_f32_e32 v170, v170
	v_cvt_pk_bf16_f32 v171, v186, v187
	v_add_f32_e32 v170, 1.0, v170
	v_rcp_f32_e32 v189, v170
	v_cvt_pk_bf16_f32 v170, v172, v173
	v_cvt_pk_bf16_f32 v172, v184, v185
	v_pk_mul_f32 v[182:183], v[182:183], v[188:189]
	s_nop 0
	v_cvt_pk_bf16_f32 v173, v182, v183
	global_store_dwordx4 v[130:131], v[170:173], off
	v_pk_mul_f32 v[182:183], v[86:87], v[180:181] op_sel_hi:[1,0]
	s_nop 0
	v_pk_mul_f32 v[172:173], v[84:85], v[180:181] op_sel_hi:[1,0]
	v_pk_mul_f32 v[170:171], v[78:79], v[180:181] op_sel_hi:[1,0]
	v_mul_f32_e32 v179, 0xbfb8aa3b, v172
	v_exp_f32_e32 v179, v179
	v_pk_mul_f32 v[180:181], v[76:77], v[180:181] op_sel_hi:[1,0]
	v_add_f32_e32 v179, 1.0, v179
	v_rcp_f32_e32 v184, v179
	v_mul_f32_e32 v179, 0xbfb8aa3b, v180
	v_exp_f32_e32 v179, v179
	s_nop 0
	v_add_f32_e32 v179, 1.0, v179
	v_rcp_f32_e32 v186, v179
	v_mul_f32_e32 v179, 0xbfb8aa3b, v173
	v_exp_f32_e32 v179, v179
	s_nop 0
	v_add_f32_e32 v179, 1.0, v179
	v_rcp_f32_e32 v185, v179
	v_mul_f32_e32 v179, 0xbfb8aa3b, v181
	v_exp_f32_e32 v179, v179
	v_pk_mul_f32 v[172:173], v[172:173], v[184:185]
	v_add_f32_e32 v179, 1.0, v179
	v_rcp_f32_e32 v187, v179
	v_mul_f32_e32 v179, 0xbfb8aa3b, v182
	v_exp_f32_e32 v179, v179
	v_pk_mul_f32 v[180:181], v[180:181], v[186:187]
	v_add_f32_e32 v179, 1.0, v179
	v_rcp_f32_e32 v184, v179
	v_mul_f32_e32 v179, 0xbfb8aa3b, v170
	v_exp_f32_e32 v179, v179
	s_nop 0
	v_add_f32_e32 v179, 1.0, v179
	v_rcp_f32_e32 v186, v179
	v_mul_f32_e32 v179, 0xbfb8aa3b, v183
	v_exp_f32_e32 v179, v179
	s_nop 0
	v_add_f32_e32 v179, 1.0, v179
	v_rcp_f32_e32 v185, v179
	v_mul_f32_e32 v179, 0xbfb8aa3b, v171
	v_exp_f32_e32 v179, v179
	v_pk_mul_f32 v[182:183], v[182:183], v[184:185]
	v_add_f32_e32 v179, 1.0, v179
	v_rcp_f32_e32 v187, v179
	s_nop 0
	v_pk_mul_f32 v[184:185], v[170:171], v[186:187]
	v_cvt_pk_bf16_f32 v170, v172, v173
	v_cvt_pk_bf16_f32 v171, v182, v183
	v_cvt_pk_bf16_f32 v172, v180, v181
	v_cvt_pk_bf16_f32 v173, v184, v185
	global_store_dwordx4 v[130:131], v[170:173], off offset:256
	v_lshl_add_u64 v[130:131], v[128:129], 0, v[154:155]
	s_nop 1
	v_mov_b32_e32 v170, v239
	v_fmamk_f32 v170, v170, 0x3a800000, v175
	v_rsq_f32_e32 v180, v170
	s_nop 0
	v_pk_mul_f32 v[172:173], v[80:81], v[180:181] op_sel_hi:[1,0]
	s_nop 0
	v_mul_f32_e32 v179, 0xbfb8aa3b, v172
	v_exp_f32_e32 v179, v179
	v_pk_mul_f32 v[184:185], v[72:73], v[180:181] op_sel_hi:[1,0]
	v_pk_mul_f32 v[170:171], v[82:83], v[180:181] op_sel_hi:[1,0]
	v_pk_mul_f32 v[182:183], v[74:75], v[180:181] op_sel_hi:[1,0]
	v_add_f32_e32 v179, 1.0, v179
	v_rcp_f32_e32 v186, v179
	v_mul_f32_e32 v179, 0xbfb8aa3b, v184
	v_exp_f32_e32 v179, v179
	s_nop 0
	v_add_f32_e32 v179, 1.0, v179
	v_rcp_f32_e32 v188, v179
	v_mul_f32_e32 v179, 0xbfb8aa3b, v173
	v_exp_f32_e32 v179, v179
	s_nop 0
	v_add_f32_e32 v179, 1.0, v179
	v_rcp_f32_e32 v187, v179
	v_mul_f32_e32 v179, 0xbfb8aa3b, v185
	v_exp_f32_e32 v179, v179
	v_pk_mul_f32 v[172:173], v[172:173], v[186:187]
	v_add_f32_e32 v179, 1.0, v179
	v_rcp_f32_e32 v189, v179
	v_mul_f32_e32 v179, 0xbfb8aa3b, v170
	v_exp_f32_e32 v179, v179
	v_pk_mul_f32 v[184:185], v[184:185], v[188:189]
	v_add_f32_e32 v179, 1.0, v179
	v_rcp_f32_e32 v186, v179
	v_mul_f32_e32 v179, 0xbfb8aa3b, v182
	v_exp_f32_e32 v179, v179
	s_nop 0
	v_add_f32_e32 v179, 1.0, v179
	v_rcp_f32_e32 v188, v179
	v_mul_f32_e32 v179, 0xbfb8aa3b, v171
	v_exp_f32_e32 v179, v179
	s_nop 0
	v_add_f32_e32 v179, 1.0, v179
	v_rcp_f32_e32 v187, v179
	s_nop 0
	v_pk_mul_f32 v[186:187], v[170:171], v[186:187]
	v_mul_f32_e32 v170, 0xbfb8aa3b, v183
	v_exp_f32_e32 v170, v170
	v_cvt_pk_bf16_f32 v171, v186, v187
	v_add_f32_e32 v170, 1.0, v170
	v_rcp_f32_e32 v189, v170
	v_cvt_pk_bf16_f32 v170, v172, v173
	v_cvt_pk_bf16_f32 v172, v184, v185
	v_pk_mul_f32 v[182:183], v[182:183], v[188:189]
	s_nop 0
	v_cvt_pk_bf16_f32 v173, v182, v183
	global_store_dwordx4 v[130:131], v[170:173], off
	v_pk_mul_f32 v[182:183], v[70:71], v[180:181] op_sel_hi:[1,0]
	s_nop 0
	v_pk_mul_f32 v[172:173], v[68:69], v[180:181] op_sel_hi:[1,0]
	v_pk_mul_f32 v[170:171], v[66:67], v[180:181] op_sel_hi:[1,0]
	v_mul_f32_e32 v179, 0xbfb8aa3b, v172
	v_exp_f32_e32 v179, v179
	v_pk_mul_f32 v[180:181], v[64:65], v[180:181] op_sel_hi:[1,0]
	v_add_f32_e32 v179, 1.0, v179
	v_rcp_f32_e32 v184, v179
	v_mul_f32_e32 v179, 0xbfb8aa3b, v180
	v_exp_f32_e32 v179, v179
	s_nop 0
	v_add_f32_e32 v179, 1.0, v179
	v_rcp_f32_e32 v186, v179
	v_mul_f32_e32 v179, 0xbfb8aa3b, v173
	v_exp_f32_e32 v179, v179
	s_nop 0
	v_add_f32_e32 v179, 1.0, v179
	v_rcp_f32_e32 v185, v179
; DI unsigned pk2(float a, float b) { f32x2 v = {a, b}; bf2_t r = __builtin_convertvector(v, bf2_t); return __builtin_bit_cast(unsigned, r); }
; DI float sigm(float x) { return __builtin_amdgcn_rcpf(1.f + __expf(-x)); }
; DI float silu_(float x) { return x * __builtin_amdgcn_rcpf(1.f + __expf(-x)); }
; template <int ACT>
; DI void epi_bf16(const f32x4 (&acc)[2][2][4][2], bf16_t* O, const int ldc, int wr, int wc, int fr, int fq, const float* ssrow = nullptr) {
;     ...
;             const float rsc = ssrow ? __builtin_amdgcn_rsqf(ssrow[ai * HALF + wr * 64 + m * 16 + fr] * (1.f / 1024.f) + EPS_) : 1.f;
; #pragma unroll
;             for (int bj = 0; bj < 2; ++bj) {
;                 f32x4 v0 = acc[ai][bj][m][0] * rsc, v1 = acc[ai][bj][m][1] * rsc;
;                 if (ACT == 1) {
; #pragma unroll
;                     for (int j = 0; j < 4; ++j) { v0[j] = silu_(v0[j]); v1[j] = silu_(v1[j]); } }
;                 if (ACT == 2) {
; #pragma unroll
;                     for (int j = 0; j < 4; ++j) { v0[j] = sigm(v0[j]); v1[j] = sigm(v1[j]); } }
;                 u32x4 w; w[0] = pk2(v0[0], v0[1]); w[1] = pk2(v0[2], v0[3]); w[2] = pk2(v1[0], v1[1]); w[3] = pk2(v1[2], v1[3]);
;                 *(u32x4*)(rowp + bj * HALF) = w;
	v_mul_f32_e32 v179, 0xbfb8aa3b, v181
	v_exp_f32_e32 v179, v179
	v_pk_mul_f32 v[172:173], v[172:173], v[184:185]
	v_add_f32_e32 v179, 1.0, v179
	v_rcp_f32_e32 v187, v179
	v_mul_f32_e32 v179, 0xbfb8aa3b, v182
	v_exp_f32_e32 v179, v179
	v_pk_mul_f32 v[180:181], v[180:181], v[186:187]
	v_add_f32_e32 v179, 1.0, v179
	v_rcp_f32_e32 v184, v179
	v_mul_f32_e32 v179, 0xbfb8aa3b, v170
	v_exp_f32_e32 v179, v179
	s_nop 0
	v_add_f32_e32 v179, 1.0, v179
	v_rcp_f32_e32 v186, v179
	v_mul_f32_e32 v179, 0xbfb8aa3b, v183
	v_exp_f32_e32 v179, v179
	s_nop 0
	v_add_f32_e32 v179, 1.0, v179
	v_rcp_f32_e32 v185, v179
	v_mul_f32_e32 v179, 0xbfb8aa3b, v171
	v_exp_f32_e32 v179, v179
	v_pk_mul_f32 v[182:183], v[182:183], v[184:185]
	v_add_f32_e32 v179, 1.0, v179
	v_rcp_f32_e32 v187, v179
	s_nop 0
	v_pk_mul_f32 v[184:185], v[170:171], v[186:187]
	v_cvt_pk_bf16_f32 v170, v172, v173
	v_cvt_pk_bf16_f32 v171, v182, v183
	v_cvt_pk_bf16_f32 v172, v180, v181
	v_cvt_pk_bf16_f32 v173, v184, v185
	global_store_dwordx4 v[130:131], v[170:173], off offset:256
	v_lshl_add_u64 v[130:131], v[128:129], 0, v[156:157]
	s_nop 1
	v_mov_b32_e32 v170, v240
	v_fmamk_f32 v170, v170, 0x3a800000, v175
	v_rsq_f32_e32 v180, v170
	s_nop 0
	v_pk_mul_f32 v[172:173], v[60:61], v[180:181] op_sel_hi:[1,0]
	s_nop 0
	v_mul_f32_e32 v179, 0xbfb8aa3b, v172
	v_exp_f32_e32 v179, v179
	v_pk_mul_f32 v[184:185], v[56:57], v[180:181] op_sel_hi:[1,0]
	v_pk_mul_f32 v[170:171], v[62:63], v[180:181] op_sel_hi:[1,0]
	v_pk_mul_f32 v[182:183], v[58:59], v[180:181] op_sel_hi:[1,0]
	v_add_f32_e32 v179, 1.0, v179
	v_rcp_f32_e32 v186, v179
	v_mul_f32_e32 v179, 0xbfb8aa3b, v184
	v_exp_f32_e32 v179, v179
	s_nop 0
	v_add_f32_e32 v179, 1.0, v179
	v_rcp_f32_e32 v188, v179
	v_mul_f32_e32 v179, 0xbfb8aa3b, v173
	v_exp_f32_e32 v179, v179
	s_nop 0
	v_add_f32_e32 v179, 1.0, v179
	v_rcp_f32_e32 v187, v179
	v_mul_f32_e32 v179, 0xbfb8aa3b, v185
	v_exp_f32_e32 v179, v179
	v_pk_mul_f32 v[172:173], v[172:173], v[186:187]
	v_add_f32_e32 v179, 1.0, v179
	v_rcp_f32_e32 v189, v179
	v_mul_f32_e32 v179, 0xbfb8aa3b, v170
	v_exp_f32_e32 v179, v179
	v_pk_mul_f32 v[184:185], v[184:185], v[188:189]
	v_add_f32_e32 v179, 1.0, v179
	v_rcp_f32_e32 v186, v179
	v_mul_f32_e32 v179, 0xbfb8aa3b, v182
	v_exp_f32_e32 v179, v179
	s_nop 0
	v_add_f32_e32 v179, 1.0, v179
	v_rcp_f32_e32 v188, v179
	v_mul_f32_e32 v179, 0xbfb8aa3b, v171
	v_exp_f32_e32 v179, v179
	s_nop 0
	v_add_f32_e32 v179, 1.0, v179
	v_rcp_f32_e32 v187, v179
	s_nop 0
	v_pk_mul_f32 v[186:187], v[170:171], v[186:187]
	v_mul_f32_e32 v170, 0xbfb8aa3b, v183
	v_exp_f32_e32 v170, v170
	v_cvt_pk_bf16_f32 v171, v186, v187
	v_add_f32_e32 v170, 1.0, v170
	v_rcp_f32_e32 v189, v170
	v_cvt_pk_bf16_f32 v170, v172, v173
	v_cvt_pk_bf16_f32 v172, v184, v185
	v_pk_mul_f32 v[182:183], v[182:183], v[188:189]
	s_nop 0
	v_cvt_pk_bf16_f32 v173, v182, v183
	global_store_dwordx4 v[130:131], v[170:173], off
	v_pk_mul_f32 v[182:183], v[54:55], v[180:181] op_sel_hi:[1,0]
	s_nop 0
	v_pk_mul_f32 v[172:173], v[52:53], v[180:181] op_sel_hi:[1,0]
	v_pk_mul_f32 v[170:171], v[46:47], v[180:181] op_sel_hi:[1,0]
	v_mul_f32_e32 v179, 0xbfb8aa3b, v172
	v_exp_f32_e32 v179, v179
	v_pk_mul_f32 v[180:181], v[44:45], v[180:181] op_sel_hi:[1,0]
	v_add_f32_e32 v179, 1.0, v179
	v_rcp_f32_e32 v184, v179
	v_mul_f32_e32 v179, 0xbfb8aa3b, v180
	v_exp_f32_e32 v179, v179
	s_nop 0
	v_add_f32_e32 v179, 1.0, v179
	v_rcp_f32_e32 v186, v179
	v_mul_f32_e32 v179, 0xbfb8aa3b, v173
	v_exp_f32_e32 v179, v179
	s_nop 0
	v_add_f32_e32 v179, 1.0, v179
	v_rcp_f32_e32 v185, v179
	v_mul_f32_e32 v179, 0xbfb8aa3b, v181
	v_exp_f32_e32 v179, v179
	v_pk_mul_f32 v[172:173], v[172:173], v[184:185]
	v_add_f32_e32 v179, 1.0, v179
	v_rcp_f32_e32 v187, v179
	v_mul_f32_e32 v179, 0xbfb8aa3b, v182
	v_exp_f32_e32 v179, v179
	v_pk_mul_f32 v[180:181], v[180:181], v[186:187]
	v_add_f32_e32 v179, 1.0, v179
	v_rcp_f32_e32 v184, v179
	v_mul_f32_e32 v179, 0xbfb8aa3b, v170
	v_exp_f32_e32 v179, v179
	s_nop 0
	v_add_f32_e32 v179, 1.0, v179
	v_rcp_f32_e32 v186, v179
	v_mul_f32_e32 v179, 0xbfb8aa3b, v183
	v_exp_f32_e32 v179, v179
	s_nop 0
	v_add_f32_e32 v179, 1.0, v179
	v_rcp_f32_e32 v185, v179
	v_mul_f32_e32 v179, 0xbfb8aa3b, v171
	v_exp_f32_e32 v179, v179
	v_pk_mul_f32 v[182:183], v[182:183], v[184:185]
	v_add_f32_e32 v179, 1.0, v179
	v_rcp_f32_e32 v187, v179
	s_nop 0
	v_pk_mul_f32 v[184:185], v[170:171], v[186:187]
	v_cvt_pk_bf16_f32 v170, v172, v173
	v_cvt_pk_bf16_f32 v171, v182, v183
	v_cvt_pk_bf16_f32 v172, v180, v181
	v_cvt_pk_bf16_f32 v173, v184, v185
	global_store_dwordx4 v[130:131], v[170:173], off offset:256
	v_lshl_add_u64 v[130:131], v[128:129], 0, v[158:159]
	s_nop 1
	v_mov_b32_e32 v170, v241
	v_fmamk_f32 v170, v170, 0x3a800000, v175
	v_rsq_f32_e32 v180, v170
	s_nop 0
	v_pk_mul_f32 v[172:173], v[48:49], v[180:181] op_sel_hi:[1,0]
	s_nop 0
	v_mul_f32_e32 v179, 0xbfb8aa3b, v172
	v_exp_f32_e32 v179, v179
	v_pk_mul_f32 v[184:185], v[40:41], v[180:181] op_sel_hi:[1,0]
	v_pk_mul_f32 v[170:171], v[50:51], v[180:181] op_sel_hi:[1,0]
	v_pk_mul_f32 v[182:183], v[42:43], v[180:181] op_sel_hi:[1,0]
	v_add_f32_e32 v179, 1.0, v179
	v_rcp_f32_e32 v186, v179
	v_mul_f32_e32 v179, 0xbfb8aa3b, v184
	v_exp_f32_e32 v179, v179
	s_nop 0
	v_add_f32_e32 v179, 1.0, v179
	v_rcp_f32_e32 v188, v179
	v_mul_f32_e32 v179, 0xbfb8aa3b, v173
	v_exp_f32_e32 v179, v179
	s_nop 0
	v_add_f32_e32 v179, 1.0, v179
	v_rcp_f32_e32 v187, v179
	v_mul_f32_e32 v179, 0xbfb8aa3b, v185
	v_exp_f32_e32 v179, v179
	v_pk_mul_f32 v[172:173], v[172:173], v[186:187]
	v_add_f32_e32 v179, 1.0, v179
	v_rcp_f32_e32 v189, v179
	v_mul_f32_e32 v179, 0xbfb8aa3b, v170
	v_exp_f32_e32 v179, v179
	v_pk_mul_f32 v[184:185], v[184:185], v[188:189]
; DI unsigned pk2(float a, float b) { f32x2 v = {a, b}; bf2_t r = __builtin_convertvector(v, bf2_t); return __builtin_bit_cast(unsigned, r); }
; DI float sigm(float x) { return __builtin_amdgcn_rcpf(1.f + __expf(-x)); }
; DI float silu_(float x) { return x * __builtin_amdgcn_rcpf(1.f + __expf(-x)); }
; template <int ACT>
; DI void epi_bf16(const f32x4 (&acc)[2][2][4][2], bf16_t* O, const int ldc, int wr, int wc, int fr, int fq, const float* ssrow = nullptr) {
;     ...
;             const float rsc = ssrow ? __builtin_amdgcn_rsqf(ssrow[ai * HALF + wr * 64 + m * 16 + fr] * (1.f / 1024.f) + EPS_) : 1.f;
; #pragma unroll
;             for (int bj = 0; bj < 2; ++bj) {
;                 f32x4 v0 = acc[ai][bj][m][0] * rsc, v1 = acc[ai][bj][m][1] * rsc;
;                 if (ACT == 1) {
; #pragma unroll
;                     for (int j = 0; j < 4; ++j) { v0[j] = silu_(v0[j]); v1[j] = silu_(v1[j]); } }
;                 if (ACT == 2) {
; #pragma unroll
;                     for (int j = 0; j < 4; ++j) { v0[j] = sigm(v0[j]); v1[j] = sigm(v1[j]); } }
;                 u32x4 w; w[0] = pk2(v0[0], v0[1]); w[1] = pk2(v0[2], v0[3]); w[2] = pk2(v1[0], v1[1]); w[3] = pk2(v1[2], v1[3]);
;                 *(u32x4*)(rowp + bj * HALF) = w;
	v_add_f32_e32 v179, 1.0, v179
	v_rcp_f32_e32 v186, v179
	v_mul_f32_e32 v179, 0xbfb8aa3b, v182
	v_exp_f32_e32 v179, v179
	s_nop 0
	v_add_f32_e32 v179, 1.0, v179
	v_rcp_f32_e32 v188, v179
	v_mul_f32_e32 v179, 0xbfb8aa3b, v171
	v_exp_f32_e32 v179, v179
	s_nop 0
	v_add_f32_e32 v179, 1.0, v179
	v_rcp_f32_e32 v187, v179
	s_nop 0
	v_pk_mul_f32 v[186:187], v[170:171], v[186:187]
	v_mul_f32_e32 v170, 0xbfb8aa3b, v183
	v_exp_f32_e32 v170, v170
	v_cvt_pk_bf16_f32 v171, v186, v187
	v_add_f32_e32 v170, 1.0, v170
	v_rcp_f32_e32 v189, v170
	v_cvt_pk_bf16_f32 v170, v172, v173
	v_cvt_pk_bf16_f32 v172, v184, v185
	v_pk_mul_f32 v[182:183], v[182:183], v[188:189]
	s_nop 0
	v_cvt_pk_bf16_f32 v173, v182, v183
	global_store_dwordx4 v[130:131], v[170:173], off
	v_pk_mul_f32 v[182:183], v[38:39], v[180:181] op_sel_hi:[1,0]
	s_nop 0
	v_pk_mul_f32 v[172:173], v[36:37], v[180:181] op_sel_hi:[1,0]
	v_pk_mul_f32 v[170:171], v[30:31], v[180:181] op_sel_hi:[1,0]
	v_mul_f32_e32 v179, 0xbfb8aa3b, v172
	v_exp_f32_e32 v179, v179
	v_pk_mul_f32 v[180:181], v[28:29], v[180:181] op_sel_hi:[1,0]
	v_add_f32_e32 v179, 1.0, v179
	v_rcp_f32_e32 v184, v179
	v_mul_f32_e32 v179, 0xbfb8aa3b, v180
	v_exp_f32_e32 v179, v179
	s_nop 0
	v_add_f32_e32 v179, 1.0, v179
	v_rcp_f32_e32 v186, v179
	v_mul_f32_e32 v179, 0xbfb8aa3b, v173
	v_exp_f32_e32 v179, v179
	s_nop 0
	v_add_f32_e32 v179, 1.0, v179
	v_rcp_f32_e32 v185, v179
	v_mul_f32_e32 v179, 0xbfb8aa3b, v181
	v_exp_f32_e32 v179, v179
	v_pk_mul_f32 v[172:173], v[172:173], v[184:185]
	v_add_f32_e32 v179, 1.0, v179
	v_rcp_f32_e32 v187, v179
	v_mul_f32_e32 v179, 0xbfb8aa3b, v182
	v_exp_f32_e32 v179, v179
	v_pk_mul_f32 v[180:181], v[180:181], v[186:187]
	v_add_f32_e32 v179, 1.0, v179
	v_rcp_f32_e32 v184, v179
	v_mul_f32_e32 v179, 0xbfb8aa3b, v170
	v_exp_f32_e32 v179, v179
	s_nop 0
	v_add_f32_e32 v179, 1.0, v179
	v_rcp_f32_e32 v186, v179
	v_mul_f32_e32 v179, 0xbfb8aa3b, v183
	v_exp_f32_e32 v179, v179
	s_nop 0
	v_add_f32_e32 v179, 1.0, v179
	v_rcp_f32_e32 v185, v179
	v_mul_f32_e32 v179, 0xbfb8aa3b, v171
	v_exp_f32_e32 v179, v179
	v_pk_mul_f32 v[182:183], v[182:183], v[184:185]
	v_add_f32_e32 v179, 1.0, v179
	v_rcp_f32_e32 v187, v179
	s_nop 0
	v_pk_mul_f32 v[184:185], v[170:171], v[186:187]
	v_cvt_pk_bf16_f32 v170, v172, v173
	v_cvt_pk_bf16_f32 v171, v182, v183
	v_cvt_pk_bf16_f32 v172, v180, v181
	v_cvt_pk_bf16_f32 v173, v184, v185
	global_store_dwordx4 v[130:131], v[170:173], off offset:256
	v_lshl_add_u64 v[130:131], v[128:129], 0, v[160:161]
	s_nop 1
	v_mov_b32_e32 v170, v242
	v_fmamk_f32 v170, v170, 0x3a800000, v175
	v_rsq_f32_e32 v180, v170
	s_nop 0
	v_pk_mul_f32 v[172:173], v[32:33], v[180:181] op_sel_hi:[1,0]
	s_nop 0
	v_mul_f32_e32 v179, 0xbfb8aa3b, v172
	v_exp_f32_e32 v179, v179
	v_pk_mul_f32 v[184:185], v[24:25], v[180:181] op_sel_hi:[1,0]
	v_pk_mul_f32 v[170:171], v[34:35], v[180:181] op_sel_hi:[1,0]
	v_pk_mul_f32 v[182:183], v[26:27], v[180:181] op_sel_hi:[1,0]
	v_add_f32_e32 v179, 1.0, v179
	v_rcp_f32_e32 v186, v179
	v_mul_f32_e32 v179, 0xbfb8aa3b, v184
	v_exp_f32_e32 v179, v179
	s_nop 0
	v_add_f32_e32 v179, 1.0, v179
	v_rcp_f32_e32 v188, v179
	v_mul_f32_e32 v179, 0xbfb8aa3b, v173
	v_exp_f32_e32 v179, v179
	s_nop 0
	v_add_f32_e32 v179, 1.0, v179
	v_rcp_f32_e32 v187, v179
	v_mul_f32_e32 v179, 0xbfb8aa3b, v185
	v_exp_f32_e32 v179, v179
	v_pk_mul_f32 v[172:173], v[172:173], v[186:187]
	v_add_f32_e32 v179, 1.0, v179
	v_rcp_f32_e32 v189, v179
	v_mul_f32_e32 v179, 0xbfb8aa3b, v170
	v_exp_f32_e32 v179, v179
	v_pk_mul_f32 v[184:185], v[184:185], v[188:189]
	v_add_f32_e32 v179, 1.0, v179
	v_rcp_f32_e32 v186, v179
	v_mul_f32_e32 v179, 0xbfb8aa3b, v182
	v_exp_f32_e32 v179, v179
	s_nop 0
	v_add_f32_e32 v179, 1.0, v179
	v_rcp_f32_e32 v188, v179
	v_mul_f32_e32 v179, 0xbfb8aa3b, v171
	v_exp_f32_e32 v179, v179
	s_nop 0
	v_add_f32_e32 v179, 1.0, v179
	v_rcp_f32_e32 v187, v179
	s_nop 0
	v_pk_mul_f32 v[186:187], v[170:171], v[186:187]
	v_mul_f32_e32 v170, 0xbfb8aa3b, v183
	v_exp_f32_e32 v170, v170
	v_cvt_pk_bf16_f32 v171, v186, v187
	v_add_f32_e32 v170, 1.0, v170
	v_rcp_f32_e32 v189, v170
	v_cvt_pk_bf16_f32 v170, v172, v173
	v_cvt_pk_bf16_f32 v172, v184, v185
	v_pk_mul_f32 v[182:183], v[182:183], v[188:189]
	s_nop 0
	v_cvt_pk_bf16_f32 v173, v182, v183
	global_store_dwordx4 v[130:131], v[170:173], off
	v_pk_mul_f32 v[182:183], v[22:23], v[180:181] op_sel_hi:[1,0]
	s_nop 0
	v_pk_mul_f32 v[172:173], v[20:21], v[180:181] op_sel_hi:[1,0]
	v_pk_mul_f32 v[170:171], v[14:15], v[180:181] op_sel_hi:[1,0]
	v_mul_f32_e32 v179, 0xbfb8aa3b, v172
	v_exp_f32_e32 v179, v179
	v_pk_mul_f32 v[180:181], v[12:13], v[180:181] op_sel_hi:[1,0]
	v_add_f32_e32 v179, 1.0, v179
	v_rcp_f32_e32 v184, v179
	v_mul_f32_e32 v179, 0xbfb8aa3b, v180
	v_exp_f32_e32 v179, v179
	s_nop 0
	v_add_f32_e32 v179, 1.0, v179
	v_rcp_f32_e32 v186, v179
	v_mul_f32_e32 v179, 0xbfb8aa3b, v173
	v_exp_f32_e32 v179, v179
	s_nop 0
	v_add_f32_e32 v179, 1.0, v179
	v_rcp_f32_e32 v185, v179
	v_mul_f32_e32 v179, 0xbfb8aa3b, v181
	v_exp_f32_e32 v179, v179
	v_pk_mul_f32 v[172:173], v[172:173], v[184:185]
	v_add_f32_e32 v179, 1.0, v179
	v_rcp_f32_e32 v187, v179
	v_mul_f32_e32 v179, 0xbfb8aa3b, v182
	v_exp_f32_e32 v179, v179
	v_pk_mul_f32 v[180:181], v[180:181], v[186:187]
	v_add_f32_e32 v179, 1.0, v179
	v_rcp_f32_e32 v184, v179
	v_mul_f32_e32 v179, 0xbfb8aa3b, v170
	v_exp_f32_e32 v179, v179
	s_nop 0
	v_add_f32_e32 v179, 1.0, v179
	v_rcp_f32_e32 v186, v179
	v_mul_f32_e32 v179, 0xbfb8aa3b, v183
	v_exp_f32_e32 v179, v179
	s_nop 0
	v_add_f32_e32 v179, 1.0, v179
	v_rcp_f32_e32 v185, v179
	v_mul_f32_e32 v179, 0xbfb8aa3b, v171
	v_exp_f32_e32 v179, v179
	v_pk_mul_f32 v[182:183], v[182:183], v[184:185]
	v_add_f32_e32 v179, 1.0, v179
; DI unsigned pk2(float a, float b) { f32x2 v = {a, b}; bf2_t r = __builtin_convertvector(v, bf2_t); return __builtin_bit_cast(unsigned, r); }
; DI float sigm(float x) { return __builtin_amdgcn_rcpf(1.f + __expf(-x)); }
; DI float silu_(float x) { return x * __builtin_amdgcn_rcpf(1.f + __expf(-x)); }
; template <int ACT>
; DI void epi_bf16(const f32x4 (&acc)[2][2][4][2], bf16_t* O, const int ldc, int wr, int wc, int fr, int fq, const float* ssrow = nullptr) {
;     ...
;             const float rsc = ssrow ? __builtin_amdgcn_rsqf(ssrow[ai * HALF + wr * 64 + m * 16 + fr] * (1.f / 1024.f) + EPS_) : 1.f;
; #pragma unroll
;             for (int bj = 0; bj < 2; ++bj) {
;                 f32x4 v0 = acc[ai][bj][m][0] * rsc, v1 = acc[ai][bj][m][1] * rsc;
;                 if (ACT == 1) {
; #pragma unroll
;                     for (int j = 0; j < 4; ++j) { v0[j] = silu_(v0[j]); v1[j] = silu_(v1[j]); } }
;                 if (ACT == 2) {
; #pragma unroll
;                     for (int j = 0; j < 4; ++j) { v0[j] = sigm(v0[j]); v1[j] = sigm(v1[j]); } }
;                 u32x4 w; w[0] = pk2(v0[0], v0[1]); w[1] = pk2(v0[2], v0[3]); w[2] = pk2(v1[0], v1[1]); w[3] = pk2(v1[2], v1[3]);
;                 *(u32x4*)(rowp + bj * HALF) = w;
	v_rcp_f32_e32 v187, v179
	s_nop 0
	v_pk_mul_f32 v[184:185], v[170:171], v[186:187]
	v_cvt_pk_bf16_f32 v170, v172, v173
	v_cvt_pk_bf16_f32 v171, v182, v183
	v_cvt_pk_bf16_f32 v172, v180, v181
	v_cvt_pk_bf16_f32 v173, v184, v185
	global_store_dwordx4 v[130:131], v[170:173], off offset:256
	s_nop 1
	v_mov_b32_e32 v130, v243
	v_fmamk_f32 v130, v130, 0x3a800000, v175
	v_rsq_f32_e32 v170, v130
	v_lshl_add_u64 v[172:173], v[128:129], 0, v[162:163]
	v_pk_mul_f32 v[130:131], v[16:17], v[170:171] op_sel_hi:[1,0]
	v_pk_mul_f32 v[128:129], v[18:19], v[170:171] op_sel_hi:[1,0]
	v_pk_mul_f32 v[180:181], v[10:11], v[170:171] op_sel_hi:[1,0]
	v_pk_mul_f32 v[182:183], v[8:9], v[170:171] op_sel_hi:[1,0]
	v_mul_f32_e32 v171, 0xbfb8aa3b, v130
	v_exp_f32_e32 v171, v171
	s_nop 0
	v_add_f32_e32 v171, 1.0, v171
	v_rcp_f32_e32 v184, v171
	v_mul_f32_e32 v171, 0xbfb8aa3b, v182
	v_exp_f32_e32 v171, v171
	s_nop 0
	v_add_f32_e32 v171, 1.0, v171
	v_rcp_f32_e32 v186, v171
	v_mul_f32_e32 v171, 0xbfb8aa3b, v131
	v_exp_f32_e32 v171, v171
	s_nop 0
	v_add_f32_e32 v171, 1.0, v171
	v_rcp_f32_e32 v185, v171
	v_mul_f32_e32 v171, 0xbfb8aa3b, v183
	v_exp_f32_e32 v171, v171
	v_pk_mul_f32 v[130:131], v[130:131], v[184:185]
	v_add_f32_e32 v171, 1.0, v171
	v_rcp_f32_e32 v187, v171
	v_mul_f32_e32 v171, 0xbfb8aa3b, v128
	v_exp_f32_e32 v171, v171
	v_pk_mul_f32 v[182:183], v[182:183], v[186:187]
	v_add_f32_e32 v171, 1.0, v171
	v_rcp_f32_e32 v184, v171
	v_mul_f32_e32 v171, 0xbfb8aa3b, v180
	v_exp_f32_e32 v171, v171
	s_nop 0
	v_add_f32_e32 v171, 1.0, v171
	v_rcp_f32_e32 v186, v171
	v_mul_f32_e32 v171, 0xbfb8aa3b, v129
	v_exp_f32_e32 v171, v171
	s_nop 0
	v_add_f32_e32 v171, 1.0, v171
	v_rcp_f32_e32 v185, v171
	s_nop 0
	v_pk_mul_f32 v[184:185], v[128:129], v[184:185]
	v_mul_f32_e32 v128, 0xbfb8aa3b, v181
	v_exp_f32_e32 v128, v128
	v_cvt_pk_bf16_f32 v129, v184, v185
	v_add_f32_e32 v128, 1.0, v128
	v_rcp_f32_e32 v187, v128
	v_cvt_pk_bf16_f32 v128, v130, v131
	v_cvt_pk_bf16_f32 v130, v182, v183
	v_pk_mul_f32 v[180:181], v[180:181], v[186:187]
	s_nop 0
	v_cvt_pk_bf16_f32 v131, v180, v181
	global_store_dwordx4 v[172:173], v[128:131], off
	v_pk_mul_f32 v[172:173], v[6:7], v[170:171] op_sel_hi:[1,0]
	s_nop 0
	v_pk_mul_f32 v[130:131], v[4:5], v[170:171] op_sel_hi:[1,0]
	v_pk_mul_f32 v[128:129], v[2:3], v[170:171] op_sel_hi:[1,0]
	v_mul_f32_e32 v179, 0xbfb8aa3b, v130
	v_exp_f32_e32 v179, v179
	v_pk_mul_f32 v[170:171], v[0:1], v[170:171] op_sel_hi:[1,0]
	v_add_f32_e32 v179, 1.0, v179
	v_rcp_f32_e32 v180, v179
	v_mul_f32_e32 v179, 0xbfb8aa3b, v170
	v_exp_f32_e32 v179, v179
	s_nop 0
	v_add_f32_e32 v179, 1.0, v179
	v_rcp_f32_e32 v182, v179
	v_mul_f32_e32 v179, 0xbfb8aa3b, v131
	v_exp_f32_e32 v179, v179
	s_nop 0
	v_add_f32_e32 v179, 1.0, v179
	v_rcp_f32_e32 v181, v179
	v_mul_f32_e32 v179, 0xbfb8aa3b, v171
	v_exp_f32_e32 v179, v179
	v_pk_mul_f32 v[130:131], v[130:131], v[180:181]
	v_add_f32_e32 v179, 1.0, v179
	v_rcp_f32_e32 v183, v179
	s_nop 0
	v_pk_mul_f32 v[180:181], v[170:171], v[182:183]
	v_mul_f32_e32 v171, 0xbfb8aa3b, v128
	v_exp_f32_e32 v171, v171
	v_mul_f32_e32 v170, 0xbfb8aa3b, v172
	v_exp_f32_e32 v170, v170
	v_add_f32_e32 v171, 1.0, v171
	v_rcp_f32_e32 v182, v171
	v_mul_f32_e32 v171, 0xbfb8aa3b, v173
	v_exp_f32_e32 v171, v171
	v_add_f32_e32 v170, 1.0, v170
	v_rcp_f32_e32 v170, v170
	v_add_f32_e32 v171, 1.0, v171
	v_rcp_f32_e32 v171, v171
	s_nop 0
	v_pk_mul_f32 v[172:173], v[172:173], v[170:171]
	v_mul_f32_e32 v170, 0xbfb8aa3b, v129
	v_exp_f32_e32 v170, v170
	s_nop 0
	v_add_f32_e32 v170, 1.0, v170
	v_rcp_f32_e32 v183, v170
	s_nop 0
	v_pk_mul_f32 v[170:171], v[128:129], v[182:183]
	v_cvt_pk_bf16_f32 v128, v130, v131
	v_cvt_pk_bf16_f32 v129, v172, v173
	v_cvt_pk_bf16_f32 v130, v180, v181
.LBB0_755:
	s_andn2_b64 vcc, exec, s[2:3]
	s_cbranch_vccnz .LBB0_748
	global_load_dword v236, v[168:169], off
	global_load_dword v237, v[168:169], off offset:64
	global_load_dword v238, v[168:169], off offset:128
	global_load_dword v239, v[168:169], off offset:192
	global_load_dword v240, v[168:169], off offset:512
	global_load_dword v241, v[168:169], off offset:576
	global_load_dword v242, v[168:169], off offset:640
	global_load_dword v243, v[168:169], off offset:704
	v_readlane_b32 s2, v246, 51
	v_readlane_b32 s3, v246, 52
	s_add_u32 s4, s2, s27
	s_addc_u32 s15, s3, s15
	s_ashr_i32 s31, s30, 31
	s_lshl_b64 s[2:3], s[30:31], 1
	s_add_u32 s28, s4, s2
	s_addc_u32 s29, s15, s3
	s_lshl_b32 s2, s74, 1
	s_add_u32 s2, s28, s2
	s_addc_u32 s3, s29, 0
	s_waitcnt vmcnt(0)
; DI unsigned pk2(float a, float b) { f32x2 v = {a, b}; bf2_t r = __builtin_convertvector(v, bf2_t); return __builtin_bit_cast(unsigned, r); }
; DI float sigm(float x) { return __builtin_amdgcn_rcpf(1.f + __expf(-x)); }
; DI float silu_(float x) { return x * __builtin_amdgcn_rcpf(1.f + __expf(-x)); }
; template <int ACT>
; DI void epi_bf16(const f32x4 (&acc)[2][2][4][2], bf16_t* O, const int ldc, int wr, int wc, int fr, int fq, const float* ssrow = nullptr) {
;     ...
;             const float rsc = ssrow ? __builtin_amdgcn_rsqf(ssrow[ai * HALF + wr * 64 + m * 16 + fr] * (1.f / 1024.f) + EPS_) : 1.f;
; #pragma unroll
;             for (int bj = 0; bj < 2; ++bj) {
;                 f32x4 v0 = acc[ai][bj][m][0] * rsc, v1 = acc[ai][bj][m][1] * rsc;
;                 if (ACT == 1) {
; #pragma unroll
;                     for (int j = 0; j < 4; ++j) { v0[j] = silu_(v0[j]); v1[j] = silu_(v1[j]); } }
;                 if (ACT == 2) {
; #pragma unroll
;                     for (int j = 0; j < 4; ++j) { v0[j] = sigm(v0[j]); v1[j] = sigm(v1[j]); } }
;                 u32x4 w; w[0] = pk2(v0[0], v0[1]); w[1] = pk2(v0[2], v0[3]); w[2] = pk2(v1[0], v1[1]); w[3] = pk2(v1[2], v1[3]);
;                 *(u32x4*)(rowp + bj * HALF) = w;
	v_mov_b32_e32 v128, v236
	v_fmamk_f32 v128, v128, 0x3a800000, v175
	v_rsq_f32_e32 v130, v128
	v_lshl_add_u64 v[128:129], s[2:3], 0, v[132:133]
	v_lshl_add_u64 v[170:171], v[128:129], 0, v[148:149]
	v_pk_mul_f32 v[126:127], v[126:127], v[130:131] op_sel_hi:[1,0]
	v_pk_mul_f32 v[124:125], v[124:125], v[130:131] op_sel_hi:[1,0]
	v_pk_mul_f32 v[122:123], v[122:123], v[130:131] op_sel_hi:[1,0]
	v_pk_mul_f32 v[120:121], v[120:121], v[130:131] op_sel_hi:[1,0]
	v_pk_mul_f32 v[118:119], v[118:119], v[130:131] op_sel_hi:[1,0]
	v_pk_mul_f32 v[116:117], v[116:117], v[130:131] op_sel_hi:[1,0]
	v_pk_mul_f32 v[172:173], v[110:111], v[130:131] op_sel_hi:[1,0]
	v_pk_mul_f32 v[130:131], v[108:109], v[130:131] op_sel_hi:[1,0]
	v_cvt_pk_bf16_f32 v108, v124, v125
	v_cvt_pk_bf16_f32 v109, v126, v127
	v_cvt_pk_bf16_f32 v110, v120, v121
	v_cvt_pk_bf16_f32 v111, v122, v123
	v_cvt_pk_bf16_f32 v116, v116, v117
	v_cvt_pk_bf16_f32 v117, v118, v119
	v_cvt_pk_bf16_f32 v118, v130, v131
	v_cvt_pk_bf16_f32 v119, v172, v173
	global_store_dwordx4 v[170:171], v[108:111], off
	global_store_dwordx4 v[170:171], v[116:119], off offset:256
	v_lshl_add_u64 v[110:111], v[128:129], 0, v[150:151]
	s_nop 1
	v_mov_b32_e32 v108, v237
	v_fmamk_f32 v108, v108, 0x3a800000, v175
	v_rsq_f32_e32 v108, v108
	s_nop 0
	v_pk_mul_f32 v[114:115], v[114:115], v[108:109] op_sel_hi:[1,0]
	v_pk_mul_f32 v[112:113], v[112:113], v[108:109] op_sel_hi:[1,0]
	v_pk_mul_f32 v[106:107], v[106:107], v[108:109] op_sel_hi:[1,0]
	v_pk_mul_f32 v[104:105], v[104:105], v[108:109] op_sel_hi:[1,0]
	v_pk_mul_f32 v[102:103], v[102:103], v[108:109] op_sel_hi:[1,0]
	v_pk_mul_f32 v[100:101], v[100:101], v[108:109] op_sel_hi:[1,0]
	v_pk_mul_f32 v[116:117], v[94:95], v[108:109] op_sel_hi:[1,0]
	v_pk_mul_f32 v[108:109], v[92:93], v[108:109] op_sel_hi:[1,0]
	v_cvt_pk_bf16_f32 v92, v112, v113
	v_cvt_pk_bf16_f32 v93, v114, v115
	v_cvt_pk_bf16_f32 v94, v104, v105
	v_cvt_pk_bf16_f32 v95, v106, v107
	v_cvt_pk_bf16_f32 v100, v100, v101
	v_cvt_pk_bf16_f32 v101, v102, v103
	v_cvt_pk_bf16_f32 v102, v108, v109
	v_cvt_pk_bf16_f32 v103, v116, v117
	global_store_dwordx4 v[110:111], v[92:95], off
	global_store_dwordx4 v[110:111], v[100:103], off offset:256
	v_lshl_add_u64 v[94:95], v[128:129], 0, v[152:153]
	s_nop 1
	v_mov_b32_e32 v92, v238
	v_fmamk_f32 v92, v92, 0x3a800000, v175
	v_rsq_f32_e32 v92, v92
	s_nop 0
	v_pk_mul_f32 v[98:99], v[98:99], v[92:93] op_sel_hi:[1,0]
	v_pk_mul_f32 v[96:97], v[96:97], v[92:93] op_sel_hi:[1,0]
	v_pk_mul_f32 v[90:91], v[90:91], v[92:93] op_sel_hi:[1,0]
	v_pk_mul_f32 v[88:89], v[88:89], v[92:93] op_sel_hi:[1,0]
	v_pk_mul_f32 v[86:87], v[86:87], v[92:93] op_sel_hi:[1,0]
	v_pk_mul_f32 v[84:85], v[84:85], v[92:93] op_sel_hi:[1,0]
	v_pk_mul_f32 v[100:101], v[78:79], v[92:93] op_sel_hi:[1,0]
	v_pk_mul_f32 v[92:93], v[76:77], v[92:93] op_sel_hi:[1,0]
	v_cvt_pk_bf16_f32 v76, v96, v97
	v_cvt_pk_bf16_f32 v77, v98, v99
	v_cvt_pk_bf16_f32 v78, v88, v89
	v_cvt_pk_bf16_f32 v79, v90, v91
	v_cvt_pk_bf16_f32 v84, v84, v85
	v_cvt_pk_bf16_f32 v85, v86, v87
	v_cvt_pk_bf16_f32 v86, v92, v93
	v_cvt_pk_bf16_f32 v87, v100, v101
	global_store_dwordx4 v[94:95], v[76:79], off
	global_store_dwordx4 v[94:95], v[84:87], off offset:256
	v_lshl_add_u64 v[78:79], v[128:129], 0, v[154:155]
	s_nop 1
	v_mov_b32_e32 v76, v239
	v_fmamk_f32 v76, v76, 0x3a800000, v175
	v_rsq_f32_e32 v76, v76
	s_nop 0
	v_pk_mul_f32 v[82:83], v[82:83], v[76:77] op_sel_hi:[1,0]
	v_pk_mul_f32 v[80:81], v[80:81], v[76:77] op_sel_hi:[1,0]
	v_pk_mul_f32 v[74:75], v[74:75], v[76:77] op_sel_hi:[1,0]
	v_pk_mul_f32 v[72:73], v[72:73], v[76:77] op_sel_hi:[1,0]
	v_pk_mul_f32 v[70:71], v[70:71], v[76:77] op_sel_hi:[1,0]
	v_pk_mul_f32 v[68:69], v[68:69], v[76:77] op_sel_hi:[1,0]
	v_pk_mul_f32 v[84:85], v[66:67], v[76:77] op_sel_hi:[1,0]
	v_pk_mul_f32 v[76:77], v[64:65], v[76:77] op_sel_hi:[1,0]
	v_cvt_pk_bf16_f32 v64, v80, v81
	v_cvt_pk_bf16_f32 v65, v82, v83
	v_cvt_pk_bf16_f32 v66, v72, v73
	v_cvt_pk_bf16_f32 v67, v74, v75
	v_cvt_pk_bf16_f32 v68, v68, v69
	v_cvt_pk_bf16_f32 v69, v70, v71
	v_cvt_pk_bf16_f32 v70, v76, v77
; DI unsigned pk2(float a, float b) { f32x2 v = {a, b}; bf2_t r = __builtin_convertvector(v, bf2_t); return __builtin_bit_cast(unsigned, r); }
; DI float sigm(float x) { return __builtin_amdgcn_rcpf(1.f + __expf(-x)); }
; DI float silu_(float x) { return x * __builtin_amdgcn_rcpf(1.f + __expf(-x)); }
; template <int ACT>
; DI void epi_bf16(const f32x4 (&acc)[2][2][4][2], bf16_t* O, const int ldc, int wr, int wc, int fr, int fq, const float* ssrow = nullptr) {
;     ...
;             const float rsc = ssrow ? __builtin_amdgcn_rsqf(ssrow[ai * HALF + wr * 64 + m * 16 + fr] * (1.f / 1024.f) + EPS_) : 1.f;
; #pragma unroll
;             for (int bj = 0; bj < 2; ++bj) {
;                 f32x4 v0 = acc[ai][bj][m][0] * rsc, v1 = acc[ai][bj][m][1] * rsc;
;                 if (ACT == 1) {
; #pragma unroll
;                     for (int j = 0; j < 4; ++j) { v0[j] = silu_(v0[j]); v1[j] = silu_(v1[j]); } }
;                 if (ACT == 2) {
; #pragma unroll
;                     for (int j = 0; j < 4; ++j) { v0[j] = sigm(v0[j]); v1[j] = sigm(v1[j]); } }
;                 u32x4 w; w[0] = pk2(v0[0], v0[1]); w[1] = pk2(v0[2], v0[3]); w[2] = pk2(v1[0], v1[1]); w[3] = pk2(v1[2], v1[3]);
;                 *(u32x4*)(rowp + bj * HALF) = w;
	v_cvt_pk_bf16_f32 v71, v84, v85
	global_store_dwordx4 v[78:79], v[64:67], off
	global_store_dwordx4 v[78:79], v[68:71], off offset:256
	v_lshl_add_u64 v[66:67], v[128:129], 0, v[156:157]
	s_nop 1
	v_mov_b32_e32 v64, v240
	v_fmamk_f32 v64, v64, 0x3a800000, v175
	v_rsq_f32_e32 v64, v64
	s_nop 0
	v_pk_mul_f32 v[62:63], v[62:63], v[64:65] op_sel_hi:[1,0]
	v_pk_mul_f32 v[60:61], v[60:61], v[64:65] op_sel_hi:[1,0]
	v_pk_mul_f32 v[58:59], v[58:59], v[64:65] op_sel_hi:[1,0]
	v_pk_mul_f32 v[56:57], v[56:57], v[64:65] op_sel_hi:[1,0]
	v_pk_mul_f32 v[54:55], v[54:55], v[64:65] op_sel_hi:[1,0]
	v_pk_mul_f32 v[52:53], v[52:53], v[64:65] op_sel_hi:[1,0]
	v_pk_mul_f32 v[68:69], v[46:47], v[64:65] op_sel_hi:[1,0]
	v_pk_mul_f32 v[64:65], v[44:45], v[64:65] op_sel_hi:[1,0]
	v_cvt_pk_bf16_f32 v44, v60, v61
	v_cvt_pk_bf16_f32 v45, v62, v63
	v_cvt_pk_bf16_f32 v46, v56, v57
	v_cvt_pk_bf16_f32 v47, v58, v59
	v_cvt_pk_bf16_f32 v52, v52, v53
	v_cvt_pk_bf16_f32 v53, v54, v55
	v_cvt_pk_bf16_f32 v54, v64, v65
	v_cvt_pk_bf16_f32 v55, v68, v69
	global_store_dwordx4 v[66:67], v[44:47], off
	global_store_dwordx4 v[66:67], v[52:55], off offset:256
	v_lshl_add_u64 v[46:47], v[128:129], 0, v[158:159]
	s_nop 1
	v_mov_b32_e32 v44, v241
	v_fmamk_f32 v44, v44, 0x3a800000, v175
	v_rsq_f32_e32 v44, v44
	s_nop 0
	v_pk_mul_f32 v[50:51], v[50:51], v[44:45] op_sel_hi:[1,0]
	v_pk_mul_f32 v[48:49], v[48:49], v[44:45] op_sel_hi:[1,0]
	v_pk_mul_f32 v[42:43], v[42:43], v[44:45] op_sel_hi:[1,0]
	v_pk_mul_f32 v[40:41], v[40:41], v[44:45] op_sel_hi:[1,0]
	v_pk_mul_f32 v[38:39], v[38:39], v[44:45] op_sel_hi:[1,0]
	v_pk_mul_f32 v[36:37], v[36:37], v[44:45] op_sel_hi:[1,0]
	v_pk_mul_f32 v[52:53], v[30:31], v[44:45] op_sel_hi:[1,0]
	v_pk_mul_f32 v[44:45], v[28:29], v[44:45] op_sel_hi:[1,0]
	v_cvt_pk_bf16_f32 v28, v48, v49
	v_cvt_pk_bf16_f32 v29, v50, v51
	v_cvt_pk_bf16_f32 v30, v40, v41
	v_cvt_pk_bf16_f32 v31, v42, v43
	v_cvt_pk_bf16_f32 v36, v36, v37
	v_cvt_pk_bf16_f32 v37, v38, v39
	v_cvt_pk_bf16_f32 v38, v44, v45
	v_cvt_pk_bf16_f32 v39, v52, v53
	global_store_dwordx4 v[46:47], v[28:31], off
	global_store_dwordx4 v[46:47], v[36:39], off offset:256
	v_lshl_add_u64 v[30:31], v[128:129], 0, v[160:161]
	s_nop 1
	v_mov_b32_e32 v28, v242
	v_fmamk_f32 v28, v28, 0x3a800000, v175
	v_rsq_f32_e32 v28, v28
	s_nop 0
	v_pk_mul_f32 v[34:35], v[34:35], v[28:29] op_sel_hi:[1,0]
	v_pk_mul_f32 v[32:33], v[32:33], v[28:29] op_sel_hi:[1,0]
	v_pk_mul_f32 v[26:27], v[26:27], v[28:29] op_sel_hi:[1,0]
	v_pk_mul_f32 v[24:25], v[24:25], v[28:29] op_sel_hi:[1,0]
	v_pk_mul_f32 v[22:23], v[22:23], v[28:29] op_sel_hi:[1,0]
	v_pk_mul_f32 v[20:21], v[20:21], v[28:29] op_sel_hi:[1,0]
	v_pk_mul_f32 v[36:37], v[14:15], v[28:29] op_sel_hi:[1,0]
	v_pk_mul_f32 v[28:29], v[12:13], v[28:29] op_sel_hi:[1,0]
	v_cvt_pk_bf16_f32 v12, v32, v33
	v_cvt_pk_bf16_f32 v13, v34, v35
	v_cvt_pk_bf16_f32 v14, v24, v25
	v_cvt_pk_bf16_f32 v15, v26, v27
	v_cvt_pk_bf16_f32 v20, v20, v21
	v_cvt_pk_bf16_f32 v21, v22, v23
	v_cvt_pk_bf16_f32 v22, v28, v29
	v_cvt_pk_bf16_f32 v23, v36, v37
	global_store_dwordx4 v[30:31], v[12:15], off
	global_store_dwordx4 v[30:31], v[20:23], off offset:256
	v_lshl_add_u64 v[14:15], v[128:129], 0, v[162:163]
	s_nop 1
	v_mov_b32_e32 v12, v243
	v_fmamk_f32 v12, v12, 0x3a800000, v175
	v_rsq_f32_e32 v12, v12
	s_nop 0
	v_pk_mul_f32 v[18:19], v[18:19], v[12:13] op_sel_hi:[1,0]
	v_pk_mul_f32 v[16:17], v[16:17], v[12:13] op_sel_hi:[1,0]
	v_pk_mul_f32 v[10:11], v[10:11], v[12:13] op_sel_hi:[1,0]
	v_pk_mul_f32 v[8:9], v[8:9], v[12:13] op_sel_hi:[1,0]
	v_pk_mul_f32 v[6:7], v[6:7], v[12:13] op_sel_hi:[1,0]
	v_pk_mul_f32 v[4:5], v[4:5], v[12:13] op_sel_hi:[1,0]
	v_pk_mul_f32 v[170:171], v[2:3], v[12:13] op_sel_hi:[1,0]
	v_pk_mul_f32 v[12:13], v[0:1], v[12:13] op_sel_hi:[1,0]
	v_cvt_pk_bf16_f32 v0, v16, v17
	v_cvt_pk_bf16_f32 v1, v18, v19
	v_cvt_pk_bf16_f32 v2, v8, v9
	v_cvt_pk_bf16_f32 v3, v10, v11
	v_cvt_pk_bf16_f32 v128, v4, v5
	v_cvt_pk_bf16_f32 v129, v6, v7
	v_cvt_pk_bf16_f32 v130, v12, v13
	global_store_dwordx4 v[14:15], v[0:3], off
	s_branch .LBB0_748
